# plus: m0/s_nop reorder in GEMM DMA issue; attention 2nd half-step QK region rescheduled (14 K-fragment slots, counted lgkmcnt, VALU interleaved)
# baseline (speedup 1.0000x reference)
; #define PG8_STAGE(bufoff, gbase, voff) do { _Pragma("unroll") for (int _i = 0; _i < 2; ++_i) \
;         __builtin_amdgcn_global_load_lds((const unsigned*)((const char*)(gbase) + (voff)[_i]), (PG8_LAS unsigned*)(lds + (bufoff) + ldsw + _i * 8192), 16, 0, 0); } while (0)
; #define PG8_LDA(dst, b, h) do { _Pragma("unroll") for (int m = 0; m < 4; ++m) _Pragma("unroll") for (int k = 0; k < 2; ++k) dst[m][k] = *(const PG8_LAS bf16x8*)(lds + PG8_SA(b, h) + aoff + m * 2048 + k * 1024); } while (0)
; #define PG8_LDB(dst, b, h) do { _Pragma("unroll") for (int n = 0; n < 2; ++n) _Pragma("unroll") for (int k = 0; k < 2; ++k) dst[n][k] = *(const PG8_LAS bf16x8*)(lds + PG8_SB(b, h) + boff + n * 2048 + k * 1024); } while (0)
; #define PG8_MMA(ai, bj, At, Bt) do { __builtin_amdgcn_s_setprio(1); _Pragma("unroll") for (int m = 0; m < 4; ++m) _Pragma("unroll") for (int n = 0; n < 2; ++n) _Pragma("unroll") for (int k = 0; k < 2; ++k) \
;         acc[ai][bj][m][n] = __builtin_amdgcn_mfma_f32_16x16x32_bf16(Bt[n][k], At[m][k], acc[ai][bj][m][n], 0, 0, 0); __builtin_amdgcn_s_setprio(0); } while (0)
; #define PG8_WAIT_V(n) asm volatile("s_waitcnt vmcnt(" #n ")" ::: "memory")
; #define PG8_WAIT_L(n) asm volatile("s_waitcnt lgkmcnt(" #n ")" ::: "memory")
; #define PG8_BAR __builtin_amdgcn_s_barrier()
; #define PG8_SCHED __builtin_amdgcn_sched_barrier(0)
; template <class Epi, class Sched, bool ALIGN_EPI = true>
; __device__ __forceinline__ void gemm_phase(PG8_LAS unsigned char* lds, const int K, const Sched& S, const Epi& E) {
;     ...
;             const bool last = (t == nt - 2);
;             const char* a1 = cA + (size_t)(t + 1) * kstep;
;             const char* a2 = last ? nA : cA + (size_t)(t + 2) * kstep; const char* b2 = last ? nB : cB + (size_t)(t + 2) * kstep;
;             const char* a3 = a2 + kstep; const char* b3 = b2 + kstep;
;             PG8_LDB(B0, 0, 0); PG8_LDB(B1, 0, 1); PG8_SCHED; PG8_LDA(At, 0, 0); PG8_STAGE(PG8_SA(1, 1), a1 + hstep, voffA);
;             PG8_WAIT_V(8); PG8_WAIT_L(0); PG8_BAR; PG8_MMA(0, 0, At, B0); PG8_MMA(0, 1, At, B1); PG8_BAR; PG8_SCHED;
;             PG8_LDA(At, 0, 1); PG8_STAGE(PG8_SB(0, 0), b2, voffB); PG8_STAGE(PG8_SB(0, 1), b2 + hstep, voffB); PG8_STAGE(PG8_SA(0, 0), a2, voffA);
;             PG8_WAIT_V(8); PG8_WAIT_L(0); PG8_BAR; PG8_MMA(1, 0, At, B0); PG8_MMA(1, 1, At, B1); PG8_BAR; PG8_SCHED;
.LBB0_178:
	ds_read_b128 v[158:161], v143
	ds_read_b128 v[164:167], v143 offset:1024
	ds_read_b128 v[168:171], v143 offset:2048
	ds_read_b128 v[172:175], v143 offset:3072
	ds_read_b128 v[176:179], v145
	ds_read_b128 v[180:183], v145 offset:1024
	ds_read_b128 v[184:187], v145 offset:2048
	ds_read_b128 v[188:191], v145 offset:3072
	s_add_u32 s82, s4, 0xfffc0080
	s_addc_u32 s83, s5, -1
	s_cmp_eq_u32 s87, 12
	s_cselect_b32 s85, s75, s83
	s_cselect_b32 s84, s74, s82
	s_cselect_b32 s83, s8, s86
	s_cselect_b32 s82, s79, s81
	v_lshl_add_u64 v[224:225], s[4:5], 0, v[150:151]
	s_add_i32 m0, s95, 0xc000
	ds_read_b128 v[192:195], v163
	ds_read_b128 v[196:199], v163 offset:1024
	ds_read_b128 v[200:203], v163 offset:2048
	ds_read_b128 v[204:207], v163 offset:3072
	ds_read_b128 v[208:211], v163 offset:4096
	ds_read_b128 v[212:215], v163 offset:5120
	ds_read_b128 v[216:219], v163 offset:6144
	ds_read_b128 v[220:223], v163 offset:7168
	global_load_lds_dwordx4 v[224:225], off
	s_add_i32 m0, s95, 0xe000
	v_lshl_add_u64 v[224:225], s[4:5], 0, v[152:153]
	global_load_lds_dwordx4 v[224:225], off
	s_waitcnt vmcnt(8)
	s_waitcnt lgkmcnt(0)
	s_barrier
	s_setprio 1
	s_waitcnt lgkmcnt(0)
	v_mfma_f32_16x16x32_bf16 v[126:129], v[158:161], v[192:195], v[126:129]
	v_mfma_f32_16x16x32_bf16 v[122:125], v[168:171], v[192:195], v[122:125]
	v_mfma_f32_16x16x32_bf16 v[110:113], v[158:161], v[200:203], v[110:113]
	v_mfma_f32_16x16x32_bf16 v[106:109], v[168:171], v[200:203], v[106:109]
	v_mfma_f32_16x16x32_bf16 v[94:97], v[158:161], v[208:211], v[94:97]
	v_mfma_f32_16x16x32_bf16 v[90:93], v[168:171], v[208:211], v[90:93]
	v_mfma_f32_16x16x32_bf16 v[78:81], v[158:161], v[216:219], v[78:81]
	v_mfma_f32_16x16x32_bf16 v[74:77], v[168:171], v[216:219], v[74:77]
	v_mfma_f32_16x16x32_bf16 v[126:129], v[164:167], v[196:199], v[126:129]
	v_mfma_f32_16x16x32_bf16 v[122:125], v[172:175], v[196:199], v[122:125]
	v_mfma_f32_16x16x32_bf16 v[110:113], v[164:167], v[204:207], v[110:113]
	v_mfma_f32_16x16x32_bf16 v[106:109], v[172:175], v[204:207], v[106:109]
	v_mfma_f32_16x16x32_bf16 v[94:97], v[164:167], v[212:215], v[94:97]
	v_mfma_f32_16x16x32_bf16 v[90:93], v[172:175], v[212:215], v[90:93]
	v_mfma_f32_16x16x32_bf16 v[78:81], v[164:167], v[220:223], v[78:81]
	v_mfma_f32_16x16x32_bf16 v[74:77], v[172:175], v[220:223], v[74:77]
	v_mfma_f32_16x16x32_bf16 v[118:121], v[176:179], v[192:195], v[118:121]
	v_mfma_f32_16x16x32_bf16 v[114:117], v[184:187], v[192:195], v[114:117]
	v_mfma_f32_16x16x32_bf16 v[102:105], v[176:179], v[200:203], v[102:105]
	v_mfma_f32_16x16x32_bf16 v[98:101], v[184:187], v[200:203], v[98:101]
	v_mfma_f32_16x16x32_bf16 v[86:89], v[176:179], v[208:211], v[86:89]
	v_mfma_f32_16x16x32_bf16 v[82:85], v[184:187], v[208:211], v[82:85]
	v_mfma_f32_16x16x32_bf16 v[70:73], v[176:179], v[216:219], v[70:73]
	v_mfma_f32_16x16x32_bf16 v[66:69], v[184:187], v[216:219], v[66:69]
	v_mfma_f32_16x16x32_bf16 v[118:121], v[180:183], v[196:199], v[118:121]
	v_mfma_f32_16x16x32_bf16 v[114:117], v[188:191], v[196:199], v[114:117]
	v_mfma_f32_16x16x32_bf16 v[102:105], v[180:183], v[204:207], v[102:105]
	v_mfma_f32_16x16x32_bf16 v[98:101], v[188:191], v[204:207], v[98:101]
	v_mfma_f32_16x16x32_bf16 v[86:89], v[180:183], v[212:215], v[86:89]
	v_mfma_f32_16x16x32_bf16 v[82:85], v[188:191], v[212:215], v[82:85]
	v_mfma_f32_16x16x32_bf16 v[70:73], v[180:183], v[220:223], v[70:73]
	v_mfma_f32_16x16x32_bf16 v[66:69], v[188:191], v[220:223], v[66:69]
	s_setprio 0
	s_barrier
	s_add_i32 vcc_lo, s44, s94
	v_lshl_add_u64 v[224:225], s[82:83], 0, v[132:133]
	s_mov_b32 m0, vcc_lo
	ds_read_b128 v[192:195], v163 offset:16384
	ds_read_b128 v[196:199], v163 offset:17408
	ds_read_b128 v[200:203], v163 offset:18432
	ds_read_b128 v[204:207], v163 offset:19456
	ds_read_b128 v[208:211], v163 offset:20480
	ds_read_b128 v[212:215], v163 offset:21504
	ds_read_b128 v[216:219], v163 offset:22528
	ds_read_b128 v[220:223], v163 offset:23552
	global_load_lds_dwordx4 v[224:225], off
	s_add_i32 m0, vcc_lo, 0x2000
	s_add_u32 vcc_lo, s82, 0x40000
	v_lshl_add_u64 v[226:227], s[82:83], 0, v[136:137]
	s_addc_u32 vcc_hi, s83, 0
	s_add_i32 s59, s45, s94
	global_load_lds_dwordx4 v[226:227], off
	v_lshl_add_u64 v[228:229], vcc, 0, v[132:133]
	s_mov_b32 m0, s59
	v_lshl_add_u64 v[230:231], s[84:85], 0, v[134:135]
	global_load_lds_dwordx4 v[228:229], off
	s_add_i32 m0, s59, 0x2000
	v_lshl_add_u64 v[228:229], vcc, 0, v[136:137]
	global_load_lds_dwordx4 v[228:229], off
	s_mov_b32 m0, s95
	v_lshl_add_u64 v[228:229], s[84:85], 0, v[130:131]
	global_load_lds_dwordx4 v[228:229], off
	s_mov_b32 m0, s96
	s_nop 0
	global_load_lds_dwordx4 v[230:231], off
	s_waitcnt vmcnt(8)
	s_waitcnt lgkmcnt(0)
	s_barrier
; #define PG8_STAGE(bufoff, gbase, voff) do { _Pragma("unroll") for (int _i = 0; _i < 2; ++_i) \
;         __builtin_amdgcn_global_load_lds((const unsigned*)((const char*)(gbase) + (voff)[_i]), (PG8_LAS unsigned*)(lds + (bufoff) + ldsw + _i * 8192), 16, 0, 0); } while (0)
; #define PG8_LDA(dst, b, h) do { _Pragma("unroll") for (int m = 0; m < 4; ++m) _Pragma("unroll") for (int k = 0; k < 2; ++k) dst[m][k] = *(const PG8_LAS bf16x8*)(lds + PG8_SA(b, h) + aoff + m * 2048 + k * 1024); } while (0)
; #define PG8_LDB(dst, b, h) do { _Pragma("unroll") for (int n = 0; n < 2; ++n) _Pragma("unroll") for (int k = 0; k < 2; ++k) dst[n][k] = *(const PG8_LAS bf16x8*)(lds + PG8_SB(b, h) + boff + n * 2048 + k * 1024); } while (0)
; #define PG8_MMA(ai, bj, At, Bt) do { __builtin_amdgcn_s_setprio(1); _Pragma("unroll") for (int m = 0; m < 4; ++m) _Pragma("unroll") for (int n = 0; n < 2; ++n) _Pragma("unroll") for (int k = 0; k < 2; ++k) \
;         acc[ai][bj][m][n] = __builtin_amdgcn_mfma_f32_16x16x32_bf16(Bt[n][k], At[m][k], acc[ai][bj][m][n], 0, 0, 0); __builtin_amdgcn_s_setprio(0); } while (0)
; #define PG8_WAIT_V(n) asm volatile("s_waitcnt vmcnt(" #n ")" ::: "memory")
; #define PG8_WAIT_L(n) asm volatile("s_waitcnt lgkmcnt(" #n ")" ::: "memory")
; #define PG8_BAR __builtin_amdgcn_s_barrier()
; #define PG8_SCHED __builtin_amdgcn_sched_barrier(0)
; template <class Epi, class Sched, bool ALIGN_EPI = true>
; __device__ __forceinline__ void gemm_phase(PG8_LAS unsigned char* lds, const int K, const Sched& S, const Epi& E) {
;     ...
;             PG8_WAIT_V(8); PG8_WAIT_L(0); PG8_BAR; PG8_MMA(1, 0, At, B0); PG8_MMA(1, 1, At, B1); PG8_BAR; PG8_SCHED;
;             PG8_LDB(B0, 1, 0); PG8_LDB(B1, 1, 1); PG8_SCHED; PG8_LDA(At, 1, 0); PG8_STAGE(PG8_SA(0, 1), a2 + hstep, voffA);
;             PG8_WAIT_V(8); PG8_WAIT_L(0); PG8_BAR; PG8_MMA(0, 0, At, B0); PG8_MMA(0, 1, At, B1); PG8_BAR; PG8_SCHED;
	s_setprio 1
	s_waitcnt lgkmcnt(0)
	v_mfma_f32_16x16x32_bf16 v[62:65], v[158:161], v[192:195], v[62:65]
	v_mfma_f32_16x16x32_bf16 v[58:61], v[168:171], v[192:195], v[58:61]
	v_mfma_f32_16x16x32_bf16 v[46:49], v[158:161], v[200:203], v[46:49]
	v_mfma_f32_16x16x32_bf16 v[42:45], v[168:171], v[200:203], v[42:45]
	v_mfma_f32_16x16x32_bf16 v[30:33], v[158:161], v[208:211], v[30:33]
	v_mfma_f32_16x16x32_bf16 v[26:29], v[168:171], v[208:211], v[26:29]
	v_mfma_f32_16x16x32_bf16 v[14:17], v[158:161], v[216:219], v[14:17]
	v_mfma_f32_16x16x32_bf16 v[10:13], v[168:171], v[216:219], v[10:13]
	v_mfma_f32_16x16x32_bf16 v[62:65], v[164:167], v[196:199], v[62:65]
	v_mfma_f32_16x16x32_bf16 v[58:61], v[172:175], v[196:199], v[58:61]
	v_mfma_f32_16x16x32_bf16 v[46:49], v[164:167], v[204:207], v[46:49]
	v_mfma_f32_16x16x32_bf16 v[42:45], v[172:175], v[204:207], v[42:45]
	v_mfma_f32_16x16x32_bf16 v[30:33], v[164:167], v[212:215], v[30:33]
	v_mfma_f32_16x16x32_bf16 v[26:29], v[172:175], v[212:215], v[26:29]
	v_mfma_f32_16x16x32_bf16 v[14:17], v[164:167], v[220:223], v[14:17]
	v_mfma_f32_16x16x32_bf16 v[10:13], v[172:175], v[220:223], v[10:13]
	v_mfma_f32_16x16x32_bf16 v[54:57], v[176:179], v[192:195], v[54:57]
	v_mfma_f32_16x16x32_bf16 v[50:53], v[184:187], v[192:195], v[50:53]
	v_mfma_f32_16x16x32_bf16 v[38:41], v[176:179], v[200:203], v[38:41]
	v_mfma_f32_16x16x32_bf16 v[34:37], v[184:187], v[200:203], v[34:37]
	v_mfma_f32_16x16x32_bf16 v[22:25], v[176:179], v[208:211], v[22:25]
	v_mfma_f32_16x16x32_bf16 v[18:21], v[184:187], v[208:211], v[18:21]
	v_mfma_f32_16x16x32_bf16 v[6:9], v[176:179], v[216:219], v[6:9]
	v_mfma_f32_16x16x32_bf16 v[2:5], v[184:187], v[216:219], v[2:5]
	v_mfma_f32_16x16x32_bf16 v[54:57], v[180:183], v[196:199], v[54:57]
	v_mfma_f32_16x16x32_bf16 v[50:53], v[188:191], v[196:199], v[50:53]
	v_mfma_f32_16x16x32_bf16 v[38:41], v[180:183], v[204:207], v[38:41]
	v_mfma_f32_16x16x32_bf16 v[34:37], v[188:191], v[204:207], v[34:37]
	v_mfma_f32_16x16x32_bf16 v[22:25], v[180:183], v[212:215], v[22:25]
	v_mfma_f32_16x16x32_bf16 v[18:21], v[188:191], v[212:215], v[18:21]
	v_mfma_f32_16x16x32_bf16 v[6:9], v[180:183], v[220:223], v[6:9]
	v_mfma_f32_16x16x32_bf16 v[2:5], v[188:191], v[220:223], v[2:5]
	s_setprio 0
	s_barrier
	s_add_i32 s59, 0, 0x18000
	v_add_u32_e32 v138, s59, v1
	s_add_i32 vcc_lo, 0, 0x1c000
	ds_read_b128 v[158:161], v138
	ds_read_b128 v[164:167], v138 offset:1024
	ds_read_b128 v[168:171], v138 offset:2048
	ds_read_b128 v[172:175], v138 offset:3072
	v_add_u32_e32 v138, vcc_lo, v1
	ds_read_b128 v[176:179], v138
	ds_read_b128 v[180:183], v138 offset:1024
	ds_read_b128 v[184:187], v138 offset:2048
	ds_read_b128 v[188:191], v138 offset:3072
	s_add_u32 s84, s84, 0x40000
	s_addc_u32 s85, s85, 0
	s_mov_b32 m0, s97
	v_lshl_add_u64 v[232:233], s[84:85], 0, v[130:131]
	ds_read_b128 v[192:195], v163 offset:32768
	ds_read_b128 v[196:199], v163 offset:33792
	ds_read_b128 v[200:203], v163 offset:34816
	ds_read_b128 v[204:207], v163 offset:35840
	ds_read_b128 v[208:211], v163 offset:36864
	ds_read_b128 v[212:215], v163 offset:37888
	ds_read_b128 v[216:219], v163 offset:38912
	ds_read_b128 v[220:223], v163 offset:39936
	global_load_lds_dwordx4 v[232:233], off
	s_mov_b32 m0, s58
	v_lshl_add_u64 v[232:233], s[84:85], 0, v[134:135]
	global_load_lds_dwordx4 v[232:233], off
	s_waitcnt vmcnt(8)
	s_waitcnt lgkmcnt(0)
	s_barrier
	s_setprio 1
	s_waitcnt lgkmcnt(0)
	v_mfma_f32_16x16x32_bf16 v[126:129], v[158:161], v[192:195], v[126:129]
	v_mfma_f32_16x16x32_bf16 v[122:125], v[168:171], v[192:195], v[122:125]
	v_mfma_f32_16x16x32_bf16 v[110:113], v[158:161], v[200:203], v[110:113]
	v_mfma_f32_16x16x32_bf16 v[106:109], v[168:171], v[200:203], v[106:109]
	v_mfma_f32_16x16x32_bf16 v[94:97], v[158:161], v[208:211], v[94:97]
	v_mfma_f32_16x16x32_bf16 v[90:93], v[168:171], v[208:211], v[90:93]
	v_mfma_f32_16x16x32_bf16 v[78:81], v[158:161], v[216:219], v[78:81]
	v_mfma_f32_16x16x32_bf16 v[74:77], v[168:171], v[216:219], v[74:77]
	v_mfma_f32_16x16x32_bf16 v[126:129], v[164:167], v[196:199], v[126:129]
	v_mfma_f32_16x16x32_bf16 v[122:125], v[172:175], v[196:199], v[122:125]
	v_mfma_f32_16x16x32_bf16 v[110:113], v[164:167], v[204:207], v[110:113]
	v_mfma_f32_16x16x32_bf16 v[106:109], v[172:175], v[204:207], v[106:109]
	v_mfma_f32_16x16x32_bf16 v[94:97], v[164:167], v[212:215], v[94:97]
	v_mfma_f32_16x16x32_bf16 v[90:93], v[172:175], v[212:215], v[90:93]
	v_mfma_f32_16x16x32_bf16 v[78:81], v[164:167], v[220:223], v[78:81]
	v_mfma_f32_16x16x32_bf16 v[74:77], v[172:175], v[220:223], v[74:77]
	v_mfma_f32_16x16x32_bf16 v[118:121], v[176:179], v[192:195], v[118:121]
	v_mfma_f32_16x16x32_bf16 v[114:117], v[184:187], v[192:195], v[114:117]
	v_mfma_f32_16x16x32_bf16 v[102:105], v[176:179], v[200:203], v[102:105]
	v_mfma_f32_16x16x32_bf16 v[98:101], v[184:187], v[200:203], v[98:101]
	v_mfma_f32_16x16x32_bf16 v[86:89], v[176:179], v[208:211], v[86:89]
	v_mfma_f32_16x16x32_bf16 v[82:85], v[184:187], v[208:211], v[82:85]
	v_mfma_f32_16x16x32_bf16 v[70:73], v[176:179], v[216:219], v[70:73]
	v_mfma_f32_16x16x32_bf16 v[66:69], v[184:187], v[216:219], v[66:69]
	v_mfma_f32_16x16x32_bf16 v[118:121], v[180:183], v[196:199], v[118:121]
	v_mfma_f32_16x16x32_bf16 v[114:117], v[188:191], v[196:199], v[114:117]
	v_mfma_f32_16x16x32_bf16 v[102:105], v[180:183], v[204:207], v[102:105]
	v_mfma_f32_16x16x32_bf16 v[98:101], v[188:191], v[204:207], v[98:101]
	v_mfma_f32_16x16x32_bf16 v[86:89], v[180:183], v[212:215], v[86:89]
	v_mfma_f32_16x16x32_bf16 v[82:85], v[188:191], v[212:215], v[82:85]
	v_mfma_f32_16x16x32_bf16 v[70:73], v[180:183], v[220:223], v[70:73]
	v_mfma_f32_16x16x32_bf16 v[66:69], v[188:191], v[220:223], v[66:69]
	s_setprio 0
	s_barrier
; #define PG8_STAGE(bufoff, gbase, voff) do { _Pragma("unroll") for (int _i = 0; _i < 2; ++_i) \
;         __builtin_amdgcn_global_load_lds((const unsigned*)((const char*)(gbase) + (voff)[_i]), (PG8_LAS unsigned*)(lds + (bufoff) + ldsw + _i * 8192), 16, 0, 0); } while (0)
; #define PG8_LDA(dst, b, h) do { _Pragma("unroll") for (int m = 0; m < 4; ++m) _Pragma("unroll") for (int k = 0; k < 2; ++k) dst[m][k] = *(const PG8_LAS bf16x8*)(lds + PG8_SA(b, h) + aoff + m * 2048 + k * 1024); } while (0)
; #define PG8_MMA(ai, bj, At, Bt) do { __builtin_amdgcn_s_setprio(1); _Pragma("unroll") for (int m = 0; m < 4; ++m) _Pragma("unroll") for (int n = 0; n < 2; ++n) _Pragma("unroll") for (int k = 0; k < 2; ++k) \
;         acc[ai][bj][m][n] = __builtin_amdgcn_mfma_f32_16x16x32_bf16(Bt[n][k], At[m][k], acc[ai][bj][m][n], 0, 0, 0); __builtin_amdgcn_s_setprio(0); } while (0)
; #define PG8_WAIT_V(n) asm volatile("s_waitcnt vmcnt(" #n ")" ::: "memory")
; #define PG8_WAIT_L(n) asm volatile("s_waitcnt lgkmcnt(" #n ")" ::: "memory")
; #define PG8_BAR __builtin_amdgcn_s_barrier()
; #define PG8_SCHED __builtin_amdgcn_sched_barrier(0)
; template <class Epi, class Sched, bool ALIGN_EPI = true>
; __device__ __forceinline__ void gemm_phase(PG8_LAS unsigned char* lds, const int K, const Sched& S, const Epi& E) {
;     ...
;             PG8_LDA(At, 1, 1); PG8_STAGE(PG8_SB(1, 0), b3, voffB); PG8_STAGE(PG8_SB(1, 1), b3 + hstep, voffB); PG8_STAGE(PG8_SA(1, 0), a3, voffA);
;             PG8_WAIT_V(8); PG8_WAIT_L(0); PG8_BAR; PG8_MMA(1, 0, At, B0); PG8_MMA(1, 1, At, B1); PG8_BAR; PG8_SCHED;
;         }
;         if constexpr (Epi::TOUCH) asm volatile("" :: "v"(td));
;         if constexpr (ALIGN_EPI) { if (wr == 0) PG8_BAR; }
	s_add_i32 s59, s59, s94
	v_lshl_add_u64 v[224:225], v[224:225], 0, s[12:13]
	s_mov_b32 m0, s59
	ds_read_b128 v[192:195], v163 offset:49152
	ds_read_b128 v[196:199], v163 offset:50176
	ds_read_b128 v[200:203], v163 offset:51200
	ds_read_b128 v[204:207], v163 offset:52224
	ds_read_b128 v[208:211], v163 offset:53248
	ds_read_b128 v[212:215], v163 offset:54272
	ds_read_b128 v[216:219], v163 offset:55296
	ds_read_b128 v[220:223], v163 offset:56320
	global_load_lds_dwordx4 v[224:225], off
	s_add_i32 m0, s59, 0x2000
	s_add_u32 s82, s82, 0x40080
	v_lshl_add_u64 v[224:225], v[226:227], 0, s[12:13]
	s_addc_u32 s83, s83, 0
	s_add_i32 s59, vcc_lo, s94
	global_load_lds_dwordx4 v[224:225], off
	s_mov_b32 m0, s59
	v_lshl_add_u64 v[224:225], s[82:83], 0, v[132:133]
	global_load_lds_dwordx4 v[224:225], off
	s_add_i32 m0, s59, 0x2000
	v_lshl_add_u64 v[224:225], s[82:83], 0, v[136:137]
	global_load_lds_dwordx4 v[224:225], off
	s_mov_b32 m0, s91
	v_lshl_add_u64 v[224:225], v[228:229], 0, s[12:13]
	global_load_lds_dwordx4 v[224:225], off
	s_mov_b32 m0, s92
	v_lshl_add_u64 v[224:225], v[230:231], 0, s[12:13]
	global_load_lds_dwordx4 v[224:225], off
	s_waitcnt vmcnt(8)
	s_waitcnt lgkmcnt(0)
	s_barrier
	s_setprio 1
	s_waitcnt lgkmcnt(0)
	v_mfma_f32_16x16x32_bf16 v[62:65], v[158:161], v[192:195], v[62:65]
	v_mfma_f32_16x16x32_bf16 v[58:61], v[168:171], v[192:195], v[58:61]
	v_mfma_f32_16x16x32_bf16 v[46:49], v[158:161], v[200:203], v[46:49]
	v_mfma_f32_16x16x32_bf16 v[42:45], v[168:171], v[200:203], v[42:45]
	v_mfma_f32_16x16x32_bf16 v[30:33], v[158:161], v[208:211], v[30:33]
	v_mfma_f32_16x16x32_bf16 v[26:29], v[168:171], v[208:211], v[26:29]
	v_mfma_f32_16x16x32_bf16 v[14:17], v[158:161], v[216:219], v[14:17]
	v_mfma_f32_16x16x32_bf16 v[10:13], v[168:171], v[216:219], v[10:13]
	v_mfma_f32_16x16x32_bf16 v[62:65], v[164:167], v[196:199], v[62:65]
	v_mfma_f32_16x16x32_bf16 v[58:61], v[172:175], v[196:199], v[58:61]
	v_mfma_f32_16x16x32_bf16 v[46:49], v[164:167], v[204:207], v[46:49]
	v_mfma_f32_16x16x32_bf16 v[42:45], v[172:175], v[204:207], v[42:45]
	v_mfma_f32_16x16x32_bf16 v[30:33], v[164:167], v[212:215], v[30:33]
	v_mfma_f32_16x16x32_bf16 v[26:29], v[172:175], v[212:215], v[26:29]
	v_mfma_f32_16x16x32_bf16 v[14:17], v[164:167], v[220:223], v[14:17]
	v_mfma_f32_16x16x32_bf16 v[10:13], v[172:175], v[220:223], v[10:13]
	v_mfma_f32_16x16x32_bf16 v[54:57], v[176:179], v[192:195], v[54:57]
	v_mfma_f32_16x16x32_bf16 v[50:53], v[184:187], v[192:195], v[50:53]
	v_mfma_f32_16x16x32_bf16 v[38:41], v[176:179], v[200:203], v[38:41]
	v_mfma_f32_16x16x32_bf16 v[34:37], v[184:187], v[200:203], v[34:37]
	v_mfma_f32_16x16x32_bf16 v[22:25], v[176:179], v[208:211], v[22:25]
	v_mfma_f32_16x16x32_bf16 v[18:21], v[184:187], v[208:211], v[18:21]
	v_mfma_f32_16x16x32_bf16 v[6:9], v[176:179], v[216:219], v[6:9]
	v_mfma_f32_16x16x32_bf16 v[2:5], v[184:187], v[216:219], v[2:5]
	v_mfma_f32_16x16x32_bf16 v[54:57], v[180:183], v[196:199], v[54:57]
	v_mfma_f32_16x16x32_bf16 v[50:53], v[188:191], v[196:199], v[50:53]
	v_mfma_f32_16x16x32_bf16 v[38:41], v[180:183], v[204:207], v[38:41]
	v_mfma_f32_16x16x32_bf16 v[34:37], v[188:191], v[204:207], v[34:37]
	v_mfma_f32_16x16x32_bf16 v[22:25], v[180:183], v[212:215], v[22:25]
	v_mfma_f32_16x16x32_bf16 v[18:21], v[188:191], v[212:215], v[18:21]
	v_mfma_f32_16x16x32_bf16 v[6:9], v[180:183], v[220:223], v[6:9]
	v_mfma_f32_16x16x32_bf16 v[2:5], v[188:191], v[220:223], v[2:5]
	s_setprio 0
	s_barrier
	s_add_i32 s87, s87, 2
	s_add_u32 s4, s4, 0x100
	s_addc_u32 s5, s5, 0
	s_add_u32 s81, s81, 0x100
	s_addc_u32 s86, s86, 0
	s_cmp_gt_u32 s87, 13
	s_cbranch_scc0 .LBB0_178
	s_and_b64 vcc, exec, s[14:15]
	s_cbranch_vccz .LBB0_181
	s_barrier

; #define PG8_STAGE(bufoff, gbase, voff) do { _Pragma("unroll") for (int _i = 0; _i < 2; ++_i) \
;         __builtin_amdgcn_global_load_lds((const unsigned*)((const char*)(gbase) + (voff)[_i]), (PG8_LAS unsigned*)(lds + (bufoff) + ldsw + _i * 8192), 16, 0, 0); } while (0)
; #define PG8_LDA(dst, b, h) do { _Pragma("unroll") for (int m = 0; m < 4; ++m) _Pragma("unroll") for (int k = 0; k < 2; ++k) dst[m][k] = *(const PG8_LAS bf16x8*)(lds + PG8_SA(b, h) + aoff + m * 2048 + k * 1024); } while (0)
; #define PG8_LDB(dst, b, h) do { _Pragma("unroll") for (int n = 0; n < 2; ++n) _Pragma("unroll") for (int k = 0; k < 2; ++k) dst[n][k] = *(const PG8_LAS bf16x8*)(lds + PG8_SB(b, h) + boff + n * 2048 + k * 1024); } while (0)
; #define PG8_MMA(ai, bj, At, Bt) do { __builtin_amdgcn_s_setprio(1); _Pragma("unroll") for (int m = 0; m < 4; ++m) _Pragma("unroll") for (int n = 0; n < 2; ++n) _Pragma("unroll") for (int k = 0; k < 2; ++k) \
;         acc[ai][bj][m][n] = __builtin_amdgcn_mfma_f32_16x16x32_bf16(Bt[n][k], At[m][k], acc[ai][bj][m][n], 0, 0, 0); __builtin_amdgcn_s_setprio(0); } while (0)
; #define PG8_WAIT_V(n) asm volatile("s_waitcnt vmcnt(" #n ")" ::: "memory")
; #define PG8_WAIT_L(n) asm volatile("s_waitcnt lgkmcnt(" #n ")" ::: "memory")
; #define PG8_BAR __builtin_amdgcn_s_barrier()
; #define PG8_SCHED __builtin_amdgcn_sched_barrier(0)
; template <class Epi, class Sched, bool ALIGN_EPI = true>
; __device__ __forceinline__ void gemm_phase(PG8_LAS unsigned char* lds, const int K, const Sched& S, const Epi& E) {
;     ...
;             const bool last = (t == nt - 2);
;             const char* a1 = cA + (size_t)(t + 1) * kstep;
;             const char* a2 = last ? nA : cA + (size_t)(t + 2) * kstep; const char* b2 = last ? nB : cB + (size_t)(t + 2) * kstep;
;             const char* a3 = a2 + kstep; const char* b3 = b2 + kstep;
;             PG8_LDB(B0, 0, 0); PG8_LDB(B1, 0, 1); PG8_SCHED; PG8_LDA(At, 0, 0); PG8_STAGE(PG8_SA(1, 1), a1 + hstep, voffA);
;             PG8_WAIT_V(8); PG8_WAIT_L(0); PG8_BAR; PG8_MMA(0, 0, At, B0); PG8_MMA(0, 1, At, B1); PG8_BAR; PG8_SCHED;
;             PG8_LDA(At, 0, 1); PG8_STAGE(PG8_SB(0, 0), b2, voffB); PG8_STAGE(PG8_SB(0, 1), b2 + hstep, voffB); PG8_STAGE(PG8_SA(0, 0), a2, voffA);
;             PG8_WAIT_V(8); PG8_WAIT_L(0); PG8_BAR; PG8_MMA(1, 0, At, B0); PG8_MMA(1, 1, At, B1); PG8_BAR; PG8_SCHED;
.LBB0_1156:
	ds_read_b128 v[158:161], v143
	ds_read_b128 v[164:167], v143 offset:1024
	ds_read_b128 v[168:171], v143 offset:2048
	ds_read_b128 v[172:175], v143 offset:3072
	ds_read_b128 v[176:179], v145
	ds_read_b128 v[180:183], v145 offset:1024
	ds_read_b128 v[184:187], v145 offset:2048
	ds_read_b128 v[188:191], v145 offset:3072
	s_add_u32 s72, s6, 0xfffc0080
	s_addc_u32 s73, s7, -1
	s_cmp_eq_u32 s76, 12
	s_cselect_b32 s75, s65, s73
	s_cselect_b32 s74, s64, s72
	s_cselect_b32 s73, s16, s71
	s_cselect_b32 s72, s39, s69
	v_lshl_add_u64 v[224:225], s[6:7], 0, v[150:151]
	s_add_i32 m0, s81, 0xc000
	ds_read_b128 v[192:195], v163
	ds_read_b128 v[196:199], v163 offset:1024
	ds_read_b128 v[200:203], v163 offset:2048
	ds_read_b128 v[204:207], v163 offset:3072
	ds_read_b128 v[208:211], v163 offset:4096
	ds_read_b128 v[212:215], v163 offset:5120
	ds_read_b128 v[216:219], v163 offset:6144
	ds_read_b128 v[220:223], v163 offset:7168
	global_load_lds_dwordx4 v[224:225], off
	s_add_i32 m0, s81, 0xe000
	v_lshl_add_u64 v[224:225], s[6:7], 0, v[152:153]
	global_load_lds_dwordx4 v[224:225], off
	s_waitcnt vmcnt(8)
	s_waitcnt lgkmcnt(0)
	s_barrier
	s_setprio 1
	s_waitcnt lgkmcnt(0)
	v_mfma_f32_16x16x32_bf16 v[126:129], v[158:161], v[192:195], v[126:129]
	v_mfma_f32_16x16x32_bf16 v[122:125], v[168:171], v[192:195], v[122:125]
	v_mfma_f32_16x16x32_bf16 v[110:113], v[158:161], v[200:203], v[110:113]
	v_mfma_f32_16x16x32_bf16 v[106:109], v[168:171], v[200:203], v[106:109]
	v_mfma_f32_16x16x32_bf16 v[94:97], v[158:161], v[208:211], v[94:97]
	v_mfma_f32_16x16x32_bf16 v[90:93], v[168:171], v[208:211], v[90:93]
	v_mfma_f32_16x16x32_bf16 v[78:81], v[158:161], v[216:219], v[78:81]
	v_mfma_f32_16x16x32_bf16 v[74:77], v[168:171], v[216:219], v[74:77]
	v_mfma_f32_16x16x32_bf16 v[126:129], v[164:167], v[196:199], v[126:129]
	v_mfma_f32_16x16x32_bf16 v[122:125], v[172:175], v[196:199], v[122:125]
	v_mfma_f32_16x16x32_bf16 v[110:113], v[164:167], v[204:207], v[110:113]
	v_mfma_f32_16x16x32_bf16 v[106:109], v[172:175], v[204:207], v[106:109]
	v_mfma_f32_16x16x32_bf16 v[94:97], v[164:167], v[212:215], v[94:97]
	v_mfma_f32_16x16x32_bf16 v[90:93], v[172:175], v[212:215], v[90:93]
	v_mfma_f32_16x16x32_bf16 v[78:81], v[164:167], v[220:223], v[78:81]
	v_mfma_f32_16x16x32_bf16 v[74:77], v[172:175], v[220:223], v[74:77]
	v_mfma_f32_16x16x32_bf16 v[118:121], v[176:179], v[192:195], v[118:121]
	v_mfma_f32_16x16x32_bf16 v[114:117], v[184:187], v[192:195], v[114:117]
	v_mfma_f32_16x16x32_bf16 v[102:105], v[176:179], v[200:203], v[102:105]
	v_mfma_f32_16x16x32_bf16 v[98:101], v[184:187], v[200:203], v[98:101]
	v_mfma_f32_16x16x32_bf16 v[86:89], v[176:179], v[208:211], v[86:89]
	v_mfma_f32_16x16x32_bf16 v[82:85], v[184:187], v[208:211], v[82:85]
	v_mfma_f32_16x16x32_bf16 v[70:73], v[176:179], v[216:219], v[70:73]
	v_mfma_f32_16x16x32_bf16 v[66:69], v[184:187], v[216:219], v[66:69]
	v_mfma_f32_16x16x32_bf16 v[118:121], v[180:183], v[196:199], v[118:121]
	v_mfma_f32_16x16x32_bf16 v[114:117], v[188:191], v[196:199], v[114:117]
	v_mfma_f32_16x16x32_bf16 v[102:105], v[180:183], v[204:207], v[102:105]
	v_mfma_f32_16x16x32_bf16 v[98:101], v[188:191], v[204:207], v[98:101]
	v_mfma_f32_16x16x32_bf16 v[86:89], v[180:183], v[212:215], v[86:89]
	v_mfma_f32_16x16x32_bf16 v[82:85], v[188:191], v[212:215], v[82:85]
	v_mfma_f32_16x16x32_bf16 v[70:73], v[180:183], v[220:223], v[70:73]
	v_mfma_f32_16x16x32_bf16 v[66:69], v[188:191], v[220:223], v[66:69]
	s_setprio 0
	s_barrier
	s_add_i32 s77, s58, s80
	v_lshl_add_u64 v[224:225], s[72:73], 0, v[132:133]
	s_mov_b32 m0, s77
	ds_read_b128 v[192:195], v163 offset:16384
	ds_read_b128 v[196:199], v163 offset:17408
	ds_read_b128 v[200:203], v163 offset:18432
	ds_read_b128 v[204:207], v163 offset:19456
	ds_read_b128 v[208:211], v163 offset:20480
	ds_read_b128 v[212:215], v163 offset:21504
	ds_read_b128 v[216:219], v163 offset:22528
	ds_read_b128 v[220:223], v163 offset:23552
	global_load_lds_dwordx4 v[224:225], off
	s_add_i32 m0, s77, 0x2000
	s_add_u32 vcc_lo, s72, 0x40000
	v_lshl_add_u64 v[226:227], s[72:73], 0, v[136:137]
	s_addc_u32 vcc_hi, s73, 0
	s_add_i32 s77, s59, s80
	global_load_lds_dwordx4 v[226:227], off
	v_lshl_add_u64 v[228:229], vcc, 0, v[132:133]
	s_mov_b32 m0, s77
	v_lshl_add_u64 v[230:231], s[74:75], 0, v[134:135]
	global_load_lds_dwordx4 v[228:229], off
	s_add_i32 m0, s77, 0x2000
	v_lshl_add_u64 v[228:229], vcc, 0, v[136:137]
	global_load_lds_dwordx4 v[228:229], off
	s_mov_b32 m0, s81
	v_lshl_add_u64 v[228:229], s[74:75], 0, v[130:131]
	global_load_lds_dwordx4 v[228:229], off
	s_mov_b32 m0, s82
	s_nop 0
	global_load_lds_dwordx4 v[230:231], off
	s_waitcnt vmcnt(8)
	s_waitcnt lgkmcnt(0)
	s_barrier
; #define PG8_STAGE(bufoff, gbase, voff) do { _Pragma("unroll") for (int _i = 0; _i < 2; ++_i) \
;         __builtin_amdgcn_global_load_lds((const unsigned*)((const char*)(gbase) + (voff)[_i]), (PG8_LAS unsigned*)(lds + (bufoff) + ldsw + _i * 8192), 16, 0, 0); } while (0)
; #define PG8_LDA(dst, b, h) do { _Pragma("unroll") for (int m = 0; m < 4; ++m) _Pragma("unroll") for (int k = 0; k < 2; ++k) dst[m][k] = *(const PG8_LAS bf16x8*)(lds + PG8_SA(b, h) + aoff + m * 2048 + k * 1024); } while (0)
; #define PG8_LDB(dst, b, h) do { _Pragma("unroll") for (int n = 0; n < 2; ++n) _Pragma("unroll") for (int k = 0; k < 2; ++k) dst[n][k] = *(const PG8_LAS bf16x8*)(lds + PG8_SB(b, h) + boff + n * 2048 + k * 1024); } while (0)
; #define PG8_MMA(ai, bj, At, Bt) do { __builtin_amdgcn_s_setprio(1); _Pragma("unroll") for (int m = 0; m < 4; ++m) _Pragma("unroll") for (int n = 0; n < 2; ++n) _Pragma("unroll") for (int k = 0; k < 2; ++k) \
;         acc[ai][bj][m][n] = __builtin_amdgcn_mfma_f32_16x16x32_bf16(Bt[n][k], At[m][k], acc[ai][bj][m][n], 0, 0, 0); __builtin_amdgcn_s_setprio(0); } while (0)
; #define PG8_WAIT_V(n) asm volatile("s_waitcnt vmcnt(" #n ")" ::: "memory")
; #define PG8_WAIT_L(n) asm volatile("s_waitcnt lgkmcnt(" #n ")" ::: "memory")
; #define PG8_BAR __builtin_amdgcn_s_barrier()
; #define PG8_SCHED __builtin_amdgcn_sched_barrier(0)
; template <class Epi, class Sched, bool ALIGN_EPI = true>
; __device__ __forceinline__ void gemm_phase(PG8_LAS unsigned char* lds, const int K, const Sched& S, const Epi& E) {
;     ...
;             PG8_WAIT_V(8); PG8_WAIT_L(0); PG8_BAR; PG8_MMA(1, 0, At, B0); PG8_MMA(1, 1, At, B1); PG8_BAR; PG8_SCHED;
;             PG8_LDB(B0, 1, 0); PG8_LDB(B1, 1, 1); PG8_SCHED; PG8_LDA(At, 1, 0); PG8_STAGE(PG8_SA(0, 1), a2 + hstep, voffA);
;             PG8_WAIT_V(8); PG8_WAIT_L(0); PG8_BAR; PG8_MMA(0, 0, At, B0); PG8_MMA(0, 1, At, B1); PG8_BAR; PG8_SCHED;
	s_setprio 1
	s_waitcnt lgkmcnt(0)
	v_mfma_f32_16x16x32_bf16 v[62:65], v[158:161], v[192:195], v[62:65]
	v_mfma_f32_16x16x32_bf16 v[58:61], v[168:171], v[192:195], v[58:61]
	v_mfma_f32_16x16x32_bf16 v[46:49], v[158:161], v[200:203], v[46:49]
	v_mfma_f32_16x16x32_bf16 v[42:45], v[168:171], v[200:203], v[42:45]
	v_mfma_f32_16x16x32_bf16 v[30:33], v[158:161], v[208:211], v[30:33]
	v_mfma_f32_16x16x32_bf16 v[26:29], v[168:171], v[208:211], v[26:29]
	v_mfma_f32_16x16x32_bf16 v[14:17], v[158:161], v[216:219], v[14:17]
	v_mfma_f32_16x16x32_bf16 v[10:13], v[168:171], v[216:219], v[10:13]
	v_mfma_f32_16x16x32_bf16 v[62:65], v[164:167], v[196:199], v[62:65]
	v_mfma_f32_16x16x32_bf16 v[58:61], v[172:175], v[196:199], v[58:61]
	v_mfma_f32_16x16x32_bf16 v[46:49], v[164:167], v[204:207], v[46:49]
	v_mfma_f32_16x16x32_bf16 v[42:45], v[172:175], v[204:207], v[42:45]
	v_mfma_f32_16x16x32_bf16 v[30:33], v[164:167], v[212:215], v[30:33]
	v_mfma_f32_16x16x32_bf16 v[26:29], v[172:175], v[212:215], v[26:29]
	v_mfma_f32_16x16x32_bf16 v[14:17], v[164:167], v[220:223], v[14:17]
	v_mfma_f32_16x16x32_bf16 v[10:13], v[172:175], v[220:223], v[10:13]
	v_mfma_f32_16x16x32_bf16 v[54:57], v[176:179], v[192:195], v[54:57]
	v_mfma_f32_16x16x32_bf16 v[50:53], v[184:187], v[192:195], v[50:53]
	v_mfma_f32_16x16x32_bf16 v[38:41], v[176:179], v[200:203], v[38:41]
	v_mfma_f32_16x16x32_bf16 v[34:37], v[184:187], v[200:203], v[34:37]
	v_mfma_f32_16x16x32_bf16 v[22:25], v[176:179], v[208:211], v[22:25]
	v_mfma_f32_16x16x32_bf16 v[18:21], v[184:187], v[208:211], v[18:21]
	v_mfma_f32_16x16x32_bf16 v[6:9], v[176:179], v[216:219], v[6:9]
	v_mfma_f32_16x16x32_bf16 v[2:5], v[184:187], v[216:219], v[2:5]
	v_mfma_f32_16x16x32_bf16 v[54:57], v[180:183], v[196:199], v[54:57]
	v_mfma_f32_16x16x32_bf16 v[50:53], v[188:191], v[196:199], v[50:53]
	v_mfma_f32_16x16x32_bf16 v[38:41], v[180:183], v[204:207], v[38:41]
	v_mfma_f32_16x16x32_bf16 v[34:37], v[188:191], v[204:207], v[34:37]
	v_mfma_f32_16x16x32_bf16 v[22:25], v[180:183], v[212:215], v[22:25]
	v_mfma_f32_16x16x32_bf16 v[18:21], v[188:191], v[212:215], v[18:21]
	v_mfma_f32_16x16x32_bf16 v[6:9], v[180:183], v[220:223], v[6:9]
	v_mfma_f32_16x16x32_bf16 v[2:5], v[188:191], v[220:223], v[2:5]
	s_setprio 0
	s_barrier
	s_add_i32 s77, 0, 0x18000
	v_add_u32_e32 v138, s77, v1
	s_add_i32 vcc_lo, 0, 0x1c000
	ds_read_b128 v[158:161], v138
	ds_read_b128 v[164:167], v138 offset:1024
	ds_read_b128 v[168:171], v138 offset:2048
	ds_read_b128 v[172:175], v138 offset:3072
	v_add_u32_e32 v138, vcc_lo, v1
	ds_read_b128 v[176:179], v138
	ds_read_b128 v[180:183], v138 offset:1024
	ds_read_b128 v[184:187], v138 offset:2048
	ds_read_b128 v[188:191], v138 offset:3072
	s_add_u32 s74, s74, 0x40000
	s_addc_u32 s75, s75, 0
	s_mov_b32 m0, s83
	v_lshl_add_u64 v[232:233], s[74:75], 0, v[130:131]
	ds_read_b128 v[192:195], v163 offset:32768
	ds_read_b128 v[196:199], v163 offset:33792
	ds_read_b128 v[200:203], v163 offset:34816
	ds_read_b128 v[204:207], v163 offset:35840
	ds_read_b128 v[208:211], v163 offset:36864
	ds_read_b128 v[212:215], v163 offset:37888
	ds_read_b128 v[216:219], v163 offset:38912
	ds_read_b128 v[220:223], v163 offset:39936
	global_load_lds_dwordx4 v[232:233], off
	s_mov_b32 m0, s84
	v_lshl_add_u64 v[232:233], s[74:75], 0, v[134:135]
	global_load_lds_dwordx4 v[232:233], off
	s_waitcnt vmcnt(8)
	s_waitcnt lgkmcnt(0)
	s_barrier
	s_setprio 1
	s_waitcnt lgkmcnt(0)
	v_mfma_f32_16x16x32_bf16 v[126:129], v[158:161], v[192:195], v[126:129]
	v_mfma_f32_16x16x32_bf16 v[122:125], v[168:171], v[192:195], v[122:125]
	v_mfma_f32_16x16x32_bf16 v[110:113], v[158:161], v[200:203], v[110:113]
	v_mfma_f32_16x16x32_bf16 v[106:109], v[168:171], v[200:203], v[106:109]
	v_mfma_f32_16x16x32_bf16 v[94:97], v[158:161], v[208:211], v[94:97]
	v_mfma_f32_16x16x32_bf16 v[90:93], v[168:171], v[208:211], v[90:93]
	v_mfma_f32_16x16x32_bf16 v[78:81], v[158:161], v[216:219], v[78:81]
	v_mfma_f32_16x16x32_bf16 v[74:77], v[168:171], v[216:219], v[74:77]
	v_mfma_f32_16x16x32_bf16 v[126:129], v[164:167], v[196:199], v[126:129]
	v_mfma_f32_16x16x32_bf16 v[122:125], v[172:175], v[196:199], v[122:125]
	v_mfma_f32_16x16x32_bf16 v[110:113], v[164:167], v[204:207], v[110:113]
	v_mfma_f32_16x16x32_bf16 v[106:109], v[172:175], v[204:207], v[106:109]
	v_mfma_f32_16x16x32_bf16 v[94:97], v[164:167], v[212:215], v[94:97]
	v_mfma_f32_16x16x32_bf16 v[90:93], v[172:175], v[212:215], v[90:93]
	v_mfma_f32_16x16x32_bf16 v[78:81], v[164:167], v[220:223], v[78:81]
	v_mfma_f32_16x16x32_bf16 v[74:77], v[172:175], v[220:223], v[74:77]
	v_mfma_f32_16x16x32_bf16 v[118:121], v[176:179], v[192:195], v[118:121]
	v_mfma_f32_16x16x32_bf16 v[114:117], v[184:187], v[192:195], v[114:117]
	v_mfma_f32_16x16x32_bf16 v[102:105], v[176:179], v[200:203], v[102:105]
	v_mfma_f32_16x16x32_bf16 v[98:101], v[184:187], v[200:203], v[98:101]
	v_mfma_f32_16x16x32_bf16 v[86:89], v[176:179], v[208:211], v[86:89]
	v_mfma_f32_16x16x32_bf16 v[82:85], v[184:187], v[208:211], v[82:85]
	v_mfma_f32_16x16x32_bf16 v[70:73], v[176:179], v[216:219], v[70:73]
	v_mfma_f32_16x16x32_bf16 v[66:69], v[184:187], v[216:219], v[66:69]
	v_mfma_f32_16x16x32_bf16 v[118:121], v[180:183], v[196:199], v[118:121]
	v_mfma_f32_16x16x32_bf16 v[114:117], v[188:191], v[196:199], v[114:117]
	v_mfma_f32_16x16x32_bf16 v[102:105], v[180:183], v[204:207], v[102:105]
	v_mfma_f32_16x16x32_bf16 v[98:101], v[188:191], v[204:207], v[98:101]
	v_mfma_f32_16x16x32_bf16 v[86:89], v[180:183], v[212:215], v[86:89]
	v_mfma_f32_16x16x32_bf16 v[82:85], v[188:191], v[212:215], v[82:85]
	v_mfma_f32_16x16x32_bf16 v[70:73], v[180:183], v[220:223], v[70:73]
	v_mfma_f32_16x16x32_bf16 v[66:69], v[188:191], v[220:223], v[66:69]
	s_setprio 0
	s_barrier
; #define PG8_STAGE(bufoff, gbase, voff) do { _Pragma("unroll") for (int _i = 0; _i < 2; ++_i) \
;         __builtin_amdgcn_global_load_lds((const unsigned*)((const char*)(gbase) + (voff)[_i]), (PG8_LAS unsigned*)(lds + (bufoff) + ldsw + _i * 8192), 16, 0, 0); } while (0)
; #define PG8_LDA(dst, b, h) do { _Pragma("unroll") for (int m = 0; m < 4; ++m) _Pragma("unroll") for (int k = 0; k < 2; ++k) dst[m][k] = *(const PG8_LAS bf16x8*)(lds + PG8_SA(b, h) + aoff + m * 2048 + k * 1024); } while (0)
; #define PG8_MMA(ai, bj, At, Bt) do { __builtin_amdgcn_s_setprio(1); _Pragma("unroll") for (int m = 0; m < 4; ++m) _Pragma("unroll") for (int n = 0; n < 2; ++n) _Pragma("unroll") for (int k = 0; k < 2; ++k) \
;         acc[ai][bj][m][n] = __builtin_amdgcn_mfma_f32_16x16x32_bf16(Bt[n][k], At[m][k], acc[ai][bj][m][n], 0, 0, 0); __builtin_amdgcn_s_setprio(0); } while (0)
; #define PG8_WAIT_V(n) asm volatile("s_waitcnt vmcnt(" #n ")" ::: "memory")
; #define PG8_WAIT_L(n) asm volatile("s_waitcnt lgkmcnt(" #n ")" ::: "memory")
; #define PG8_BAR __builtin_amdgcn_s_barrier()
; #define PG8_SCHED __builtin_amdgcn_sched_barrier(0)
; template <class Epi, class Sched, bool ALIGN_EPI = true>
; __device__ __forceinline__ void gemm_phase(PG8_LAS unsigned char* lds, const int K, const Sched& S, const Epi& E) {
;     ...
;             PG8_LDA(At, 1, 1); PG8_STAGE(PG8_SB(1, 0), b3, voffB); PG8_STAGE(PG8_SB(1, 1), b3 + hstep, voffB); PG8_STAGE(PG8_SA(1, 0), a3, voffA);
;             PG8_WAIT_V(8); PG8_WAIT_L(0); PG8_BAR; PG8_MMA(1, 0, At, B0); PG8_MMA(1, 1, At, B1); PG8_BAR; PG8_SCHED;
;         }
;         if constexpr (Epi::TOUCH) asm volatile("" :: "v"(td));
;         if constexpr (ALIGN_EPI) { if (wr == 0) PG8_BAR; }
	s_add_i32 s74, s77, s80
	v_lshl_add_u64 v[224:225], v[224:225], 0, s[22:23]
	s_mov_b32 m0, s74
	ds_read_b128 v[192:195], v163 offset:49152
	ds_read_b128 v[196:199], v163 offset:50176
	ds_read_b128 v[200:203], v163 offset:51200
	ds_read_b128 v[204:207], v163 offset:52224
	ds_read_b128 v[208:211], v163 offset:53248
	ds_read_b128 v[212:215], v163 offset:54272
	ds_read_b128 v[216:219], v163 offset:55296
	ds_read_b128 v[220:223], v163 offset:56320
	global_load_lds_dwordx4 v[224:225], off
	s_add_i32 m0, s74, 0x2000
	s_add_u32 s72, s72, 0x40080
	v_lshl_add_u64 v[224:225], v[226:227], 0, s[22:23]
	s_addc_u32 s73, s73, 0
	s_add_i32 s74, vcc_lo, s80
	global_load_lds_dwordx4 v[224:225], off
	s_mov_b32 m0, s74
	v_lshl_add_u64 v[224:225], s[72:73], 0, v[132:133]
	global_load_lds_dwordx4 v[224:225], off
	s_add_i32 m0, s74, 0x2000
	v_lshl_add_u64 v[224:225], s[72:73], 0, v[136:137]
	global_load_lds_dwordx4 v[224:225], off
	s_mov_b32 m0, s92
	v_lshl_add_u64 v[224:225], v[228:229], 0, s[22:23]
	global_load_lds_dwordx4 v[224:225], off
	s_mov_b32 m0, s93
	v_lshl_add_u64 v[224:225], v[230:231], 0, s[22:23]
	global_load_lds_dwordx4 v[224:225], off
	s_waitcnt vmcnt(8)
	s_waitcnt lgkmcnt(0)
	s_barrier
	s_setprio 1
	s_waitcnt lgkmcnt(0)
	v_mfma_f32_16x16x32_bf16 v[62:65], v[158:161], v[192:195], v[62:65]
	v_mfma_f32_16x16x32_bf16 v[58:61], v[168:171], v[192:195], v[58:61]
	v_mfma_f32_16x16x32_bf16 v[46:49], v[158:161], v[200:203], v[46:49]
	v_mfma_f32_16x16x32_bf16 v[42:45], v[168:171], v[200:203], v[42:45]
	v_mfma_f32_16x16x32_bf16 v[30:33], v[158:161], v[208:211], v[30:33]
	v_mfma_f32_16x16x32_bf16 v[26:29], v[168:171], v[208:211], v[26:29]
	v_mfma_f32_16x16x32_bf16 v[14:17], v[158:161], v[216:219], v[14:17]
	v_mfma_f32_16x16x32_bf16 v[10:13], v[168:171], v[216:219], v[10:13]
	v_mfma_f32_16x16x32_bf16 v[62:65], v[164:167], v[196:199], v[62:65]
	v_mfma_f32_16x16x32_bf16 v[58:61], v[172:175], v[196:199], v[58:61]
	v_mfma_f32_16x16x32_bf16 v[46:49], v[164:167], v[204:207], v[46:49]
	v_mfma_f32_16x16x32_bf16 v[42:45], v[172:175], v[204:207], v[42:45]
	v_mfma_f32_16x16x32_bf16 v[30:33], v[164:167], v[212:215], v[30:33]
	v_mfma_f32_16x16x32_bf16 v[26:29], v[172:175], v[212:215], v[26:29]
	v_mfma_f32_16x16x32_bf16 v[14:17], v[164:167], v[220:223], v[14:17]
	v_mfma_f32_16x16x32_bf16 v[10:13], v[172:175], v[220:223], v[10:13]
	v_mfma_f32_16x16x32_bf16 v[54:57], v[176:179], v[192:195], v[54:57]
	v_mfma_f32_16x16x32_bf16 v[50:53], v[184:187], v[192:195], v[50:53]
	v_mfma_f32_16x16x32_bf16 v[38:41], v[176:179], v[200:203], v[38:41]
	v_mfma_f32_16x16x32_bf16 v[34:37], v[184:187], v[200:203], v[34:37]
	v_mfma_f32_16x16x32_bf16 v[22:25], v[176:179], v[208:211], v[22:25]
	v_mfma_f32_16x16x32_bf16 v[18:21], v[184:187], v[208:211], v[18:21]
	v_mfma_f32_16x16x32_bf16 v[6:9], v[176:179], v[216:219], v[6:9]
	v_mfma_f32_16x16x32_bf16 v[2:5], v[184:187], v[216:219], v[2:5]
	v_mfma_f32_16x16x32_bf16 v[54:57], v[180:183], v[196:199], v[54:57]
	v_mfma_f32_16x16x32_bf16 v[50:53], v[188:191], v[196:199], v[50:53]
	v_mfma_f32_16x16x32_bf16 v[38:41], v[180:183], v[204:207], v[38:41]
	v_mfma_f32_16x16x32_bf16 v[34:37], v[188:191], v[204:207], v[34:37]
	v_mfma_f32_16x16x32_bf16 v[22:25], v[180:183], v[212:215], v[22:25]
	v_mfma_f32_16x16x32_bf16 v[18:21], v[188:191], v[212:215], v[18:21]
	v_mfma_f32_16x16x32_bf16 v[6:9], v[180:183], v[220:223], v[6:9]
	v_mfma_f32_16x16x32_bf16 v[2:5], v[188:191], v[220:223], v[2:5]
	s_setprio 0
	s_barrier
	s_add_i32 s76, s76, 2
	s_add_u32 s6, s6, 0x100
	s_addc_u32 s7, s7, 0
	s_add_u32 s69, s69, 0x100
	s_addc_u32 s71, s71, 0
	s_cmp_gt_u32 s76, 13
	s_cbranch_scc0 .LBB0_1156
	s_and_b64 vcc, exec, s[24:25]
	s_cbranch_vccz .LBB0_1159
	s_barrier

; __device__ __forceinline__ void partialSM(f32x16& p0, f32x16& p1, float& m_reg, float& mn, float& alpha) {
;     ...
;     if (__builtin_expect(__all((pmax - m_reg) * SCALE <= THR), 1)) { mn = m_reg; alpha = 1.f; }
;     else { mn = fmaxf(m_reg, pmax); alpha = __builtin_amdgcn_exp2f((m_reg - mn) * C2); m_reg = mn; }
;     const float mnL = -mn * C2;
; #pragma unroll
;     for (int r = 0; r < 16; ++r) p0[r] = fmaf(p0[r], C2, mnL);
; #pragma unroll
;     for (int r = 0; r < 16; ++r) p1[r] = fmaf(p1[r], C2, mnL);
; #pragma unroll
;     for (int r = 0; r < 16; ++r) p0[r] = __builtin_amdgcn_exp2f(p0[r]);
.LBB0_1303:
	v_cndmask_b32_e64 v206, v94, v206, s[6:7]
	v_mul_f32_e32 v207, 0xbe0293ee, v206
	v_fmamk_f32 v94, v146, 0x3e0293ee, v207
	v_fmamk_f32 v82, v82, 0x3e0293ee, v207
	v_fmamk_f32 v83, v83, 0x3e0293ee, v207
	v_fmamk_f32 v95, v147, 0x3e0293ee, v207
	v_fmamk_f32 v96, v148, 0x3e0293ee, v207
	v_fmamk_f32 v97, v149, 0x3e0293ee, v207
	v_fmamk_f32 v87, v87, 0x3e0293ee, v207
	v_fmamk_f32 v88, v88, 0x3e0293ee, v207
	v_fmamk_f32 v89, v89, 0x3e0293ee, v207
	v_fmamk_f32 v90, v90, 0x3e0293ee, v207
	v_fmamk_f32 v91, v91, 0x3e0293ee, v207
	v_fmamk_f32 v92, v92, 0x3e0293ee, v207
	v_fmamk_f32 v93, v93, 0x3e0293ee, v207
	v_fmamk_f32 v79, v79, 0x3e0293ee, v207
	v_fmamk_f32 v80, v80, 0x3e0293ee, v207
	v_fmamk_f32 v81, v81, 0x3e0293ee, v207
	v_exp_f32_e32 v146, v94
	v_exp_f32_e32 v147, v82
	v_exp_f32_e32 v148, v83
	v_exp_f32_e32 v159, v95
	v_exp_f32_e32 v160, v96
	v_exp_f32_e32 v161, v97
	v_exp_f32_e32 v149, v87
	v_exp_f32_e32 v158, v88
	v_exp_f32_e32 v150, v89
	v_exp_f32_e32 v151, v90
	v_exp_f32_e32 v155, v91
	v_exp_f32_e32 v157, v92
	v_exp_f32_e32 v152, v93
	v_exp_f32_e32 v153, v79
	v_exp_f32_e32 v154, v80
	v_exp_f32_e32 v156, v81
	v_fmamk_f32 v210, v71, 0x3e0293ee, v207
	v_fmamk_f32 v209, v78, 0x3e0293ee, v207
	v_fmamk_f32 v217, v66, 0x3e0293ee, v207
	v_fmamk_f32 v218, v67, 0x3e0293ee, v207
	v_fmamk_f32 v219, v68, 0x3e0293ee, v207
	v_fmamk_f32 v220, v69, 0x3e0293ee, v207
	v_fmamk_f32 v221, v70, 0x3e0293ee, v207
	v_fmamk_f32 v211, v72, 0x3e0293ee, v207
	v_fmamk_f32 v212, v84, 0x3e0293ee, v207
	v_fmamk_f32 v213, v85, 0x3e0293ee, v207
	v_fmamk_f32 v214, v86, 0x3e0293ee, v207
	v_fmamk_f32 v215, v76, 0x3e0293ee, v207
	v_fmamk_f32 v216, v77, 0x3e0293ee, v207
	v_fmamk_f32 v222, v73, 0x3e0293ee, v207
	v_fmamk_f32 v223, v74, 0x3e0293ee, v207
	v_fmac_f32_e32 v207, 0x3e0293ee, v75
	s_waitcnt lgkmcnt(0)
	s_barrier
; __device__ __forceinline__ void finishSM(f32x16& p0, f32x16& p1, float alpha, float& l_reg, bf16x8& pa0, bf16x8& pa1, bf16x8& pa2, bf16x8& pa3) {
; #pragma unroll
;     for (int r = 0; r < 16; ++r) p1[r] = __builtin_amdgcn_exp2f(p1[r]);
;     float ps = 0;
; #pragma unroll
;     for (int r = 0; r < 16; ++r) ps += p0[r];
; #pragma unroll
;     for (int r = 0; r < 16; ++r) ps += p1[r];
;     { auto rr = __builtin_amdgcn_permlane32_swap(__float_as_uint(ps), __float_as_uint(ps), false, false);
;       ps = __uint_as_float(rr[0]) + __uint_as_float(rr[1]); }
;     l_reg = l_reg * alpha + ps;
;     ...
;     PK4(p0, 0, pa0); PK4(p0, 8, pa1); PK4(p1, 0, pa2); PK4(p1, 8, pa3);
; template <int KB>
; __device__ __forceinline__ void qkt(f32x16& p0, f32x16& p1, const char* K_lds, int r32, int hi, const bf16x8* qr) {
;     p0 = f32x16{}; p1 = f32x16{};
;     const char* kb[4];
; #pragma unroll
;     for (int dd = 0; dd < 4; ++dd) kb[dd] = K_lds + KB * SHM_K + KSWZ(r32, (dd * 16 + hi * 8) * 2);
; #pragma unroll
;     for (int d0 = 0; d0 < 8; ++d0) { const char* a = kb[d0 & 3] + (d0 >> 2) * 128;
;         bf16x8 b0 = *reinterpret_cast<const bf16x8*>(a);
;         bf16x8 b1 = *reinterpret_cast<const bf16x8*>(a + 32 * 256);
;         p0 = __builtin_amdgcn_mfma_f32_32x32x16_bf16(b0, qr[d0], p0, 0, 0, 0);
;         p1 = __builtin_amdgcn_mfma_f32_32x32x16_bf16(b1, qr[d0], p1, 0, 0, 0); }
; }
	ds_read_b128 v[66:69], v199 offset:32768
	ds_read_b128 v[70:73], v199 offset:40960
	ds_read_b128 v[172:175], v200 offset:32768
	ds_read_b128 v[224:227], v200 offset:40960
	ds_read_b128 v[130:133], v201 offset:32768
	ds_read_b128 v[134:137], v201 offset:40960
	ds_read_b128 v[138:141], v202 offset:32768
	ds_read_b128 v[142:145], v202 offset:40960
	ds_read_b128 v[228:231], v199 offset:32896
	ds_read_b128 v[232:235], v199 offset:41088
	ds_read_b128 v[236:239], v200 offset:32896
	ds_read_b128 v[240:243], v200 offset:41088
	ds_read_b128 v[244:247], v201 offset:32896
	v_exp_f32_e32 v211, v211
	v_exp_f32_e32 v212, v212
	s_waitcnt lgkmcnt(12)
	v_mfma_f32_32x32x16_bf16 v[82:97], v[66:69], v[126:129], 0
	v_exp_f32_e32 v213, v213
	v_exp_f32_e32 v214, v214
	v_exp_f32_e32 v215, v215
	s_waitcnt lgkmcnt(11)
	v_mfma_f32_32x32x16_bf16 v[66:81], v[70:73], v[126:129], 0
	v_exp_f32_e32 v216, v216
	v_exp_f32_e32 v207, v207
	s_waitcnt lgkmcnt(10)
	v_mfma_f32_32x32x16_bf16 v[82:97], v[172:175], v[122:125], v[82:97]
	ds_read_b128 v[172:175], v201 offset:41088
	v_exp_f32_e32 v250, v219
	v_exp_f32_e32 v219, v209
	v_add_f32_e32 v209, 0, v146
	v_add_f32_e32 v209, v147, v209
	s_waitcnt lgkmcnt(10)
	v_mfma_f32_32x32x16_bf16 v[66:81], v[224:227], v[122:125], v[66:81]
	ds_read_b128 v[224:227], v202 offset:32896
	v_add_f32_e32 v209, v148, v209
	v_add_f32_e32 v209, v159, v209
	v_add_f32_e32 v209, v160, v209
	v_add_f32_e32 v209, v161, v209
	v_add_f32_e32 v209, v149, v209
	s_waitcnt lgkmcnt(10)
	v_mfma_f32_32x32x16_bf16 v[82:97], v[130:133], v[118:121], v[82:97]
	ds_read_b128 v[130:133], v202 offset:41088
	v_add_f32_e32 v209, v158, v209
	v_add_f32_e32 v209, v150, v209
	v_add_f32_e32 v209, v151, v209
	v_add_f32_e32 v209, v155, v209
	v_add_f32_e32 v209, v157, v209
	s_waitcnt lgkmcnt(10)
	v_mfma_f32_32x32x16_bf16 v[66:81], v[134:137], v[118:121], v[66:81]
	v_exp_f32_e32 v248, v217
	v_add_f32_e32 v209, v152, v209
	v_exp_f32_e32 v249, v218
	s_waitcnt lgkmcnt(9)
	v_mfma_f32_32x32x16_bf16 v[82:97], v[138:141], v[114:117], v[82:97]
	v_add_f32_e32 v209, v153, v209
	v_add_f32_e32 v209, v154, v209
	v_exp_f32_e32 v251, v220
	v_add_f32_e32 v209, v156, v209
	s_waitcnt lgkmcnt(8)
	v_mfma_f32_32x32x16_bf16 v[66:81], v[142:145], v[114:117], v[66:81]
	v_exp_f32_e32 v217, v221
	v_add_f32_e32 v209, v248, v209
	v_exp_f32_e32 v218, v210
	s_waitcnt lgkmcnt(7)
	v_mfma_f32_32x32x16_bf16 v[82:97], v[228:231], v[110:113], v[82:97]
	v_add_f32_e32 v209, v249, v209
	v_add_f32_e32 v209, v250, v209
	v_add_f32_e32 v209, v251, v209
	v_add_f32_e32 v209, v217, v209
	v_add_f32_e32 v209, v218, v209
	s_waitcnt lgkmcnt(6)
	v_mfma_f32_32x32x16_bf16 v[66:81], v[232:235], v[110:113], v[66:81]
	v_add_f32_e32 v209, v211, v209
	v_add_f32_e32 v209, v212, v209
	v_add_f32_e32 v209, v213, v209
	v_exp_f32_e32 v220, v222
	s_waitcnt lgkmcnt(5)
	v_mfma_f32_32x32x16_bf16 v[82:97], v[236:239], v[106:109], v[82:97]
	v_add_f32_e32 v209, v214, v209
	v_exp_f32_e32 v221, v223
	v_add_f32_e32 v209, v215, v209
	v_add_f32_e32 v209, v216, v209
	s_waitcnt lgkmcnt(4)
	v_mfma_f32_32x32x16_bf16 v[66:81], v[240:243], v[106:109], v[66:81]
	v_add_f32_e32 v209, v219, v209
	v_add_f32_e32 v209, v220, v209
	v_add_f32_e32 v209, v221, v209
	v_add_f32_e32 v209, v207, v209
	v_mov_b32_e32 v210, v209
	s_waitcnt lgkmcnt(3)
	v_mfma_f32_32x32x16_bf16 v[82:97], v[244:247], v[102:105], v[82:97]
	v_cvt_pk_bf16_f32 v146, v146, v147
	v_cvt_pk_bf16_f32 v147, v148, v159
	v_cvt_pk_bf16_f32 v148, v160, v161
	v_cvt_pk_bf16_f32 v149, v149, v158
	v_cvt_pk_bf16_f32 v150, v150, v151
	s_waitcnt lgkmcnt(2)
	v_mfma_f32_32x32x16_bf16 v[66:81], v[172:175], v[102:105], v[66:81]
	v_cvt_pk_bf16_f32 v151, v155, v157
	v_cvt_pk_bf16_f32 v152, v152, v153
	v_cvt_pk_bf16_f32 v153, v154, v156
	v_cvt_pk_bf16_f32 v154, v248, v249
	v_cvt_pk_bf16_f32 v155, v250, v251
	s_waitcnt lgkmcnt(1)
	v_mfma_f32_32x32x16_bf16 v[82:97], v[224:227], v[98:101], v[82:97]
	v_cvt_pk_bf16_f32 v156, v217, v218
	v_cvt_pk_bf16_f32 v157, v211, v212
	v_cvt_pk_bf16_f32 v158, v213, v214
	v_cvt_pk_bf16_f32 v159, v215, v216
	v_cvt_pk_bf16_f32 v160, v219, v220
	s_waitcnt lgkmcnt(0)
	v_mfma_f32_32x32x16_bf16 v[66:81], v[130:133], v[98:101], v[66:81]
	v_cvt_pk_bf16_f32 v161, v221, v207
	v_permlane32_swap_b32_e32 v209, v210
	v_permlane32_swap_b32_e32 v146, v148
	v_permlane32_swap_b32_e32 v147, v149
	v_permlane32_swap_b32_e32 v150, v152
	v_permlane32_swap_b32_e32 v151, v153
	v_permlane32_swap_b32_e32 v154, v156
	v_permlane32_swap_b32_e32 v155, v157
	v_permlane32_swap_b32_e32 v158, v160
	v_permlane32_swap_b32_e32 v159, v161
	s_add_i32 s82, s82, 2
	s_cmp_le_u32 s82, s81
	s_cselect_b64 s[36:37], -1, 0
	s_cmp_gt_u32 s82, s81
	s_cbranch_scc1 .LBB0_1305
	v_add_co_u32_e32 v130, vcc, 0x60000, v194
	s_nop 1
	v_addc_co_u32_e32 v131, vcc, 0, v195, vcc
	v_add_co_u32_e32 v134, vcc, 0x70000, v194
	s_nop 1
	v_addc_co_u32_e32 v135, vcc, 0, v195, vcc
	v_add_co_u32_e32 v138, vcc, 0x60000, v192
	global_load_dwordx4 v[130:133], v[130:131], off
	s_nop 0
	global_load_dwordx4 v[134:137], v[134:135], off
	v_addc_co_u32_e32 v139, vcc, 0, v193, vcc
	v_add_co_u32_e32 v142, vcc, 0x70000, v192
	s_nop 1
	v_addc_co_u32_e32 v143, vcc, 0, v193, vcc
	global_load_dwordx4 v[138:141], v[138:139], off
	s_nop 0
	global_load_dwordx4 v[142:145], v[142:143], off

; #define PG8_STAGE(bufoff, gbase, voff) do { _Pragma("unroll") for (int _i = 0; _i < 2; ++_i) \
;         __builtin_amdgcn_global_load_lds((const unsigned*)((const char*)(gbase) + (voff)[_i]), (PG8_LAS unsigned*)(lds + (bufoff) + ldsw + _i * 8192), 16, 0, 0); } while (0)
; #define PG8_LDA(dst, b, h) do { _Pragma("unroll") for (int m = 0; m < 4; ++m) _Pragma("unroll") for (int k = 0; k < 2; ++k) dst[m][k] = *(const PG8_LAS bf16x8*)(lds + PG8_SA(b, h) + aoff + m * 2048 + k * 1024); } while (0)
; #define PG8_LDB(dst, b, h) do { _Pragma("unroll") for (int n = 0; n < 2; ++n) _Pragma("unroll") for (int k = 0; k < 2; ++k) dst[n][k] = *(const PG8_LAS bf16x8*)(lds + PG8_SB(b, h) + boff + n * 2048 + k * 1024); } while (0)
; #define PG8_MMA(ai, bj, At, Bt) do { __builtin_amdgcn_s_setprio(1); _Pragma("unroll") for (int m = 0; m < 4; ++m) _Pragma("unroll") for (int n = 0; n < 2; ++n) _Pragma("unroll") for (int k = 0; k < 2; ++k) \
;         acc[ai][bj][m][n] = __builtin_amdgcn_mfma_f32_16x16x32_bf16(Bt[n][k], At[m][k], acc[ai][bj][m][n], 0, 0, 0); __builtin_amdgcn_s_setprio(0); } while (0)
; #define PG8_WAIT_V(n) asm volatile("s_waitcnt vmcnt(" #n ")" ::: "memory")
; #define PG8_WAIT_L(n) asm volatile("s_waitcnt lgkmcnt(" #n ")" ::: "memory")
; #define PG8_BAR __builtin_amdgcn_s_barrier()
; #define PG8_SCHED __builtin_amdgcn_sched_barrier(0)
; template <class Epi, class Sched, bool ALIGN_EPI = true>
; __device__ __forceinline__ void gemm_phase(PG8_LAS unsigned char* lds, const int K, const Sched& S, const Epi& E) {
;     ...
;             const bool last = (t == nt - 2);
;             const char* a1 = cA + (size_t)(t + 1) * kstep;
;             const char* a2 = last ? nA : cA + (size_t)(t + 2) * kstep; const char* b2 = last ? nB : cB + (size_t)(t + 2) * kstep;
;             const char* a3 = a2 + kstep; const char* b3 = b2 + kstep;
;             PG8_LDB(B0, 0, 0); PG8_LDB(B1, 0, 1); PG8_SCHED; PG8_LDA(At, 0, 0); PG8_STAGE(PG8_SA(1, 1), a1 + hstep, voffA);
;             PG8_WAIT_V(8); PG8_WAIT_L(0); PG8_BAR; PG8_MMA(0, 0, At, B0); PG8_MMA(0, 1, At, B1); PG8_BAR; PG8_SCHED;
;             PG8_LDA(At, 0, 1); PG8_STAGE(PG8_SB(0, 0), b2, voffB); PG8_STAGE(PG8_SB(0, 1), b2 + hstep, voffB); PG8_STAGE(PG8_SA(0, 0), a2, voffA);
;             PG8_WAIT_V(8); PG8_WAIT_L(0); PG8_BAR; PG8_MMA(1, 0, At, B0); PG8_MMA(1, 1, At, B1); PG8_BAR; PG8_SCHED;
.LBB0_1515:
	v_add_u32_e32 v160, s68, v1
	ds_read_b128 v[130:133], v160
	ds_read_b128 v[134:137], v160 offset:1024
	ds_read_b128 v[138:141], v160 offset:2048
	ds_read_b128 v[164:167], v160 offset:3072
	v_add_u32_e32 v160, s69, v1
	ds_read_b128 v[168:171], v160
	ds_read_b128 v[172:175], v160 offset:1024
	ds_read_b128 v[176:179], v160 offset:2048
	ds_read_b128 v[180:183], v160 offset:3072
	s_add_u32 s46, s44, 0xfffc0080
	s_addc_u32 s47, s45, -1
	s_cmp_eq_u32 s79, 12
	s_cselect_b32 s49, s25, s47
	s_cselect_b32 s48, s41, s46
	s_cselect_b32 s47, s23, s78
	s_cselect_b32 s46, s43, s77
	v_lshl_add_u64 v[160:161], s[44:45], 0, v[152:153]
	s_add_i32 m0, s51, 0xc000
	ds_read_b128 v[184:187], v163
	ds_read_b128 v[188:191], v163 offset:1024
	ds_read_b128 v[192:195], v163 offset:2048
	ds_read_b128 v[196:199], v163 offset:3072
	ds_read_b128 v[200:203], v163 offset:4096
	ds_read_b128 v[204:207], v163 offset:5120
	ds_read_b128 v[208:211], v163 offset:6144
	ds_read_b128 v[212:215], v163 offset:7168
	global_load_lds_dwordx4 v[160:161], off
	s_add_i32 m0, s51, 0xe000
	v_lshl_add_u64 v[160:161], s[44:45], 0, v[154:155]
	global_load_lds_dwordx4 v[160:161], off
	s_waitcnt vmcnt(8)
	s_waitcnt lgkmcnt(0)
	s_barrier
	s_setprio 1
	s_waitcnt lgkmcnt(0)
	v_mfma_f32_16x16x32_bf16 v[126:129], v[130:133], v[184:187], v[126:129]
	v_mfma_f32_16x16x32_bf16 v[122:125], v[138:141], v[184:187], v[122:125]
	v_mfma_f32_16x16x32_bf16 v[118:121], v[130:133], v[192:195], v[118:121]
	v_mfma_f32_16x16x32_bf16 v[114:117], v[138:141], v[192:195], v[114:117]
	v_mfma_f32_16x16x32_bf16 v[110:113], v[130:133], v[200:203], v[110:113]
	v_mfma_f32_16x16x32_bf16 v[106:109], v[138:141], v[200:203], v[106:109]
	v_mfma_f32_16x16x32_bf16 v[102:105], v[130:133], v[208:211], v[102:105]
	v_mfma_f32_16x16x32_bf16 v[98:101], v[138:141], v[208:211], v[98:101]
	v_mfma_f32_16x16x32_bf16 v[126:129], v[134:137], v[188:191], v[126:129]
	v_mfma_f32_16x16x32_bf16 v[122:125], v[164:167], v[188:191], v[122:125]
	v_mfma_f32_16x16x32_bf16 v[118:121], v[134:137], v[196:199], v[118:121]
	v_mfma_f32_16x16x32_bf16 v[114:117], v[164:167], v[196:199], v[114:117]
	v_mfma_f32_16x16x32_bf16 v[110:113], v[134:137], v[204:207], v[110:113]
	v_mfma_f32_16x16x32_bf16 v[106:109], v[164:167], v[204:207], v[106:109]
	v_mfma_f32_16x16x32_bf16 v[102:105], v[134:137], v[212:215], v[102:105]
	v_mfma_f32_16x16x32_bf16 v[98:101], v[164:167], v[212:215], v[98:101]
	v_mfma_f32_16x16x32_bf16 v[94:97], v[168:171], v[184:187], v[94:97]
	v_mfma_f32_16x16x32_bf16 v[90:93], v[176:179], v[184:187], v[90:93]
	v_mfma_f32_16x16x32_bf16 v[86:89], v[168:171], v[192:195], v[86:89]
	v_mfma_f32_16x16x32_bf16 v[82:85], v[176:179], v[192:195], v[82:85]
	v_mfma_f32_16x16x32_bf16 v[78:81], v[168:171], v[200:203], v[78:81]
	v_mfma_f32_16x16x32_bf16 v[74:77], v[176:179], v[200:203], v[74:77]
	v_mfma_f32_16x16x32_bf16 v[70:73], v[168:171], v[208:211], v[70:73]
	v_mfma_f32_16x16x32_bf16 v[66:69], v[176:179], v[208:211], v[66:69]
	v_mfma_f32_16x16x32_bf16 v[94:97], v[172:175], v[188:191], v[94:97]
	v_mfma_f32_16x16x32_bf16 v[90:93], v[180:183], v[188:191], v[90:93]
	v_mfma_f32_16x16x32_bf16 v[86:89], v[172:175], v[196:199], v[86:89]
	v_mfma_f32_16x16x32_bf16 v[82:85], v[180:183], v[196:199], v[82:85]
	v_mfma_f32_16x16x32_bf16 v[78:81], v[172:175], v[204:207], v[78:81]
	v_mfma_f32_16x16x32_bf16 v[74:77], v[180:183], v[204:207], v[74:77]
	v_mfma_f32_16x16x32_bf16 v[70:73], v[172:175], v[212:215], v[70:73]
	v_mfma_f32_16x16x32_bf16 v[66:69], v[180:183], v[212:215], v[66:69]
	s_setprio 0
	s_barrier
	s_add_i32 s80, s68, s50
	v_lshl_add_u64 v[160:161], s[46:47], 0, v[144:145]
	s_mov_b32 m0, s80
	ds_read_b128 v[184:187], v163 offset:16384
	ds_read_b128 v[188:191], v163 offset:17408
	ds_read_b128 v[192:195], v163 offset:18432
	ds_read_b128 v[196:199], v163 offset:19456
	ds_read_b128 v[200:203], v163 offset:20480
	ds_read_b128 v[204:207], v163 offset:21504
	ds_read_b128 v[208:211], v163 offset:22528
	ds_read_b128 v[212:215], v163 offset:23552
	global_load_lds_dwordx4 v[160:161], off
	s_add_i32 m0, s80, 0x2000
	s_add_u32 s80, s46, 0x40000
	v_lshl_add_u64 v[216:217], s[46:47], 0, v[148:149]
	s_addc_u32 s81, s47, 0
	s_add_i32 s82, s69, s50
	global_load_lds_dwordx4 v[216:217], off
	v_lshl_add_u64 v[218:219], s[80:81], 0, v[144:145]
	s_mov_b32 m0, s82
	v_lshl_add_u64 v[220:221], s[48:49], 0, v[146:147]
	global_load_lds_dwordx4 v[218:219], off
	s_add_i32 m0, s82, 0x2000
	v_lshl_add_u64 v[218:219], s[80:81], 0, v[148:149]
	global_load_lds_dwordx4 v[218:219], off
	s_mov_b32 m0, s51
	v_lshl_add_u64 v[218:219], s[48:49], 0, v[142:143]
	global_load_lds_dwordx4 v[218:219], off
	s_mov_b32 m0, s56
	s_nop 0
	global_load_lds_dwordx4 v[220:221], off
	s_waitcnt vmcnt(8)
	s_waitcnt lgkmcnt(0)
	s_barrier
; #define PG8_STAGE(bufoff, gbase, voff) do { _Pragma("unroll") for (int _i = 0; _i < 2; ++_i) \
;         __builtin_amdgcn_global_load_lds((const unsigned*)((const char*)(gbase) + (voff)[_i]), (PG8_LAS unsigned*)(lds + (bufoff) + ldsw + _i * 8192), 16, 0, 0); } while (0)
; #define PG8_LDA(dst, b, h) do { _Pragma("unroll") for (int m = 0; m < 4; ++m) _Pragma("unroll") for (int k = 0; k < 2; ++k) dst[m][k] = *(const PG8_LAS bf16x8*)(lds + PG8_SA(b, h) + aoff + m * 2048 + k * 1024); } while (0)
; #define PG8_LDB(dst, b, h) do { _Pragma("unroll") for (int n = 0; n < 2; ++n) _Pragma("unroll") for (int k = 0; k < 2; ++k) dst[n][k] = *(const PG8_LAS bf16x8*)(lds + PG8_SB(b, h) + boff + n * 2048 + k * 1024); } while (0)
; #define PG8_MMA(ai, bj, At, Bt) do { __builtin_amdgcn_s_setprio(1); _Pragma("unroll") for (int m = 0; m < 4; ++m) _Pragma("unroll") for (int n = 0; n < 2; ++n) _Pragma("unroll") for (int k = 0; k < 2; ++k) \
;         acc[ai][bj][m][n] = __builtin_amdgcn_mfma_f32_16x16x32_bf16(Bt[n][k], At[m][k], acc[ai][bj][m][n], 0, 0, 0); __builtin_amdgcn_s_setprio(0); } while (0)
; #define PG8_WAIT_V(n) asm volatile("s_waitcnt vmcnt(" #n ")" ::: "memory")
; #define PG8_WAIT_L(n) asm volatile("s_waitcnt lgkmcnt(" #n ")" ::: "memory")
; #define PG8_BAR __builtin_amdgcn_s_barrier()
; #define PG8_SCHED __builtin_amdgcn_sched_barrier(0)
; template <class Epi, class Sched, bool ALIGN_EPI = true>
; __device__ __forceinline__ void gemm_phase(PG8_LAS unsigned char* lds, const int K, const Sched& S, const Epi& E) {
;     ...
;             PG8_WAIT_V(8); PG8_WAIT_L(0); PG8_BAR; PG8_MMA(1, 0, At, B0); PG8_MMA(1, 1, At, B1); PG8_BAR; PG8_SCHED;
;             PG8_LDB(B0, 1, 0); PG8_LDB(B1, 1, 1); PG8_SCHED; PG8_LDA(At, 1, 0); PG8_STAGE(PG8_SA(0, 1), a2 + hstep, voffA);
;             PG8_WAIT_V(8); PG8_WAIT_L(0); PG8_BAR; PG8_MMA(0, 0, At, B0); PG8_MMA(0, 1, At, B1); PG8_BAR; PG8_SCHED;
	s_setprio 1
	s_waitcnt lgkmcnt(0)
	v_mfma_f32_16x16x32_bf16 v[62:65], v[130:133], v[184:187], v[62:65]
	v_mfma_f32_16x16x32_bf16 v[58:61], v[138:141], v[184:187], v[58:61]
	v_mfma_f32_16x16x32_bf16 v[54:57], v[130:133], v[192:195], v[54:57]
	v_mfma_f32_16x16x32_bf16 v[50:53], v[138:141], v[192:195], v[50:53]
	v_mfma_f32_16x16x32_bf16 v[46:49], v[130:133], v[200:203], v[46:49]
	v_mfma_f32_16x16x32_bf16 v[42:45], v[138:141], v[200:203], v[42:45]
	v_mfma_f32_16x16x32_bf16 v[38:41], v[130:133], v[208:211], v[38:41]
	v_mfma_f32_16x16x32_bf16 v[34:37], v[138:141], v[208:211], v[34:37]
	v_mfma_f32_16x16x32_bf16 v[62:65], v[134:137], v[188:191], v[62:65]
	v_mfma_f32_16x16x32_bf16 v[58:61], v[164:167], v[188:191], v[58:61]
	v_mfma_f32_16x16x32_bf16 v[54:57], v[134:137], v[196:199], v[54:57]
	v_mfma_f32_16x16x32_bf16 v[50:53], v[164:167], v[196:199], v[50:53]
	v_mfma_f32_16x16x32_bf16 v[46:49], v[134:137], v[204:207], v[46:49]
	v_mfma_f32_16x16x32_bf16 v[42:45], v[164:167], v[204:207], v[42:45]
	v_mfma_f32_16x16x32_bf16 v[38:41], v[134:137], v[212:215], v[38:41]
	v_mfma_f32_16x16x32_bf16 v[34:37], v[164:167], v[212:215], v[34:37]
	v_mfma_f32_16x16x32_bf16 v[30:33], v[168:171], v[184:187], v[30:33]
	v_mfma_f32_16x16x32_bf16 v[26:29], v[176:179], v[184:187], v[26:29]
	v_mfma_f32_16x16x32_bf16 v[22:25], v[168:171], v[192:195], v[22:25]
	v_mfma_f32_16x16x32_bf16 v[18:21], v[176:179], v[192:195], v[18:21]
	v_mfma_f32_16x16x32_bf16 v[14:17], v[168:171], v[200:203], v[14:17]
	v_mfma_f32_16x16x32_bf16 v[10:13], v[176:179], v[200:203], v[10:13]
	v_mfma_f32_16x16x32_bf16 v[6:9], v[168:171], v[208:211], v[6:9]
	v_mfma_f32_16x16x32_bf16 v[2:5], v[176:179], v[208:211], v[2:5]
	v_mfma_f32_16x16x32_bf16 v[30:33], v[172:175], v[188:191], v[30:33]
	v_mfma_f32_16x16x32_bf16 v[26:29], v[180:183], v[188:191], v[26:29]
	v_mfma_f32_16x16x32_bf16 v[22:25], v[172:175], v[196:199], v[22:25]
	v_mfma_f32_16x16x32_bf16 v[18:21], v[180:183], v[196:199], v[18:21]
	v_mfma_f32_16x16x32_bf16 v[14:17], v[172:175], v[204:207], v[14:17]
	v_mfma_f32_16x16x32_bf16 v[10:13], v[180:183], v[204:207], v[10:13]
	v_mfma_f32_16x16x32_bf16 v[6:9], v[172:175], v[212:215], v[6:9]
	v_mfma_f32_16x16x32_bf16 v[2:5], v[180:183], v[212:215], v[2:5]
	s_setprio 0
	s_barrier
	s_add_i32 s80, 0, 0x18000
	s_add_i32 s81, 0, 0x1c000
	v_add_u32_e32 v164, s80, v1
	v_add_u32_e32 v180, s81, v1
	ds_read_b128 v[130:133], v164
	ds_read_b128 v[134:137], v164 offset:1024
	ds_read_b128 v[138:141], v164 offset:2048
	ds_read_b128 v[164:167], v164 offset:3072
	ds_read_b128 v[168:171], v180
	ds_read_b128 v[172:175], v180 offset:1024
	ds_read_b128 v[176:179], v180 offset:2048
	ds_read_b128 v[180:183], v180 offset:3072
	s_add_u32 s48, s48, 0x40000
	s_addc_u32 s49, s49, 0
	s_mov_b32 m0, s57
	v_lshl_add_u64 v[222:223], s[48:49], 0, v[142:143]
	ds_read_b128 v[184:187], v163 offset:32768
	ds_read_b128 v[188:191], v163 offset:33792
	ds_read_b128 v[192:195], v163 offset:34816
	ds_read_b128 v[196:199], v163 offset:35840
	ds_read_b128 v[200:203], v163 offset:36864
	ds_read_b128 v[204:207], v163 offset:37888
	ds_read_b128 v[208:211], v163 offset:38912
	ds_read_b128 v[212:215], v163 offset:39936
	global_load_lds_dwordx4 v[222:223], off
	s_mov_b32 m0, s58
	v_lshl_add_u64 v[222:223], s[48:49], 0, v[146:147]
	global_load_lds_dwordx4 v[222:223], off
	s_waitcnt vmcnt(8)
	s_waitcnt lgkmcnt(0)
	s_barrier
	s_setprio 1
	s_waitcnt lgkmcnt(0)
	v_mfma_f32_16x16x32_bf16 v[126:129], v[130:133], v[184:187], v[126:129]
	v_mfma_f32_16x16x32_bf16 v[122:125], v[138:141], v[184:187], v[122:125]
	v_mfma_f32_16x16x32_bf16 v[118:121], v[130:133], v[192:195], v[118:121]
	v_mfma_f32_16x16x32_bf16 v[114:117], v[138:141], v[192:195], v[114:117]
	v_mfma_f32_16x16x32_bf16 v[110:113], v[130:133], v[200:203], v[110:113]
	v_mfma_f32_16x16x32_bf16 v[106:109], v[138:141], v[200:203], v[106:109]
	v_mfma_f32_16x16x32_bf16 v[102:105], v[130:133], v[208:211], v[102:105]
	v_mfma_f32_16x16x32_bf16 v[98:101], v[138:141], v[208:211], v[98:101]
	v_mfma_f32_16x16x32_bf16 v[126:129], v[134:137], v[188:191], v[126:129]
	v_mfma_f32_16x16x32_bf16 v[122:125], v[164:167], v[188:191], v[122:125]
	v_mfma_f32_16x16x32_bf16 v[118:121], v[134:137], v[196:199], v[118:121]
	v_mfma_f32_16x16x32_bf16 v[114:117], v[164:167], v[196:199], v[114:117]
	v_mfma_f32_16x16x32_bf16 v[110:113], v[134:137], v[204:207], v[110:113]
	v_mfma_f32_16x16x32_bf16 v[106:109], v[164:167], v[204:207], v[106:109]
	v_mfma_f32_16x16x32_bf16 v[102:105], v[134:137], v[212:215], v[102:105]
	v_mfma_f32_16x16x32_bf16 v[98:101], v[164:167], v[212:215], v[98:101]
	v_mfma_f32_16x16x32_bf16 v[94:97], v[168:171], v[184:187], v[94:97]
	v_mfma_f32_16x16x32_bf16 v[90:93], v[176:179], v[184:187], v[90:93]
	v_mfma_f32_16x16x32_bf16 v[86:89], v[168:171], v[192:195], v[86:89]
	v_mfma_f32_16x16x32_bf16 v[82:85], v[176:179], v[192:195], v[82:85]
	v_mfma_f32_16x16x32_bf16 v[78:81], v[168:171], v[200:203], v[78:81]
	v_mfma_f32_16x16x32_bf16 v[74:77], v[176:179], v[200:203], v[74:77]
	v_mfma_f32_16x16x32_bf16 v[70:73], v[168:171], v[208:211], v[70:73]
	v_mfma_f32_16x16x32_bf16 v[66:69], v[176:179], v[208:211], v[66:69]
	v_mfma_f32_16x16x32_bf16 v[94:97], v[172:175], v[188:191], v[94:97]
	v_mfma_f32_16x16x32_bf16 v[90:93], v[180:183], v[188:191], v[90:93]
	v_mfma_f32_16x16x32_bf16 v[86:89], v[172:175], v[196:199], v[86:89]
	v_mfma_f32_16x16x32_bf16 v[82:85], v[180:183], v[196:199], v[82:85]
	v_mfma_f32_16x16x32_bf16 v[78:81], v[172:175], v[204:207], v[78:81]
	v_mfma_f32_16x16x32_bf16 v[74:77], v[180:183], v[204:207], v[74:77]
	v_mfma_f32_16x16x32_bf16 v[70:73], v[172:175], v[212:215], v[70:73]
	v_mfma_f32_16x16x32_bf16 v[66:69], v[180:183], v[212:215], v[66:69]
	s_setprio 0
	s_barrier
; #define PG8_STAGE(bufoff, gbase, voff) do { _Pragma("unroll") for (int _i = 0; _i < 2; ++_i) \
;         __builtin_amdgcn_global_load_lds((const unsigned*)((const char*)(gbase) + (voff)[_i]), (PG8_LAS unsigned*)(lds + (bufoff) + ldsw + _i * 8192), 16, 0, 0); } while (0)
; #define PG8_LDA(dst, b, h) do { _Pragma("unroll") for (int m = 0; m < 4; ++m) _Pragma("unroll") for (int k = 0; k < 2; ++k) dst[m][k] = *(const PG8_LAS bf16x8*)(lds + PG8_SA(b, h) + aoff + m * 2048 + k * 1024); } while (0)
; #define PG8_MMA(ai, bj, At, Bt) do { __builtin_amdgcn_s_setprio(1); _Pragma("unroll") for (int m = 0; m < 4; ++m) _Pragma("unroll") for (int n = 0; n < 2; ++n) _Pragma("unroll") for (int k = 0; k < 2; ++k) \
;         acc[ai][bj][m][n] = __builtin_amdgcn_mfma_f32_16x16x32_bf16(Bt[n][k], At[m][k], acc[ai][bj][m][n], 0, 0, 0); __builtin_amdgcn_s_setprio(0); } while (0)
; #define PG8_WAIT_V(n) asm volatile("s_waitcnt vmcnt(" #n ")" ::: "memory")
; #define PG8_WAIT_L(n) asm volatile("s_waitcnt lgkmcnt(" #n ")" ::: "memory")
; #define PG8_BAR __builtin_amdgcn_s_barrier()
; #define PG8_SCHED __builtin_amdgcn_sched_barrier(0)
; template <class Epi, class Sched, bool ALIGN_EPI = true>
; __device__ __forceinline__ void gemm_phase(PG8_LAS unsigned char* lds, const int K, const Sched& S, const Epi& E) {
;     ...
;             PG8_LDA(At, 1, 1); PG8_STAGE(PG8_SB(1, 0), b3, voffB); PG8_STAGE(PG8_SB(1, 1), b3 + hstep, voffB); PG8_STAGE(PG8_SA(1, 0), a3, voffA);
;             PG8_WAIT_V(8); PG8_WAIT_L(0); PG8_BAR; PG8_MMA(1, 0, At, B0); PG8_MMA(1, 1, At, B1); PG8_BAR; PG8_SCHED;
;         }
;         if constexpr (Epi::TOUCH) asm volatile("" :: "v"(td));
;         if constexpr (ALIGN_EPI) { if (wr == 0) PG8_BAR; }
	s_add_i32 s48, s80, s50
	v_lshl_add_u64 v[160:161], v[160:161], 0, s[14:15]
	s_mov_b32 m0, s48
	ds_read_b128 v[184:187], v163 offset:49152
	ds_read_b128 v[188:191], v163 offset:50176
	ds_read_b128 v[192:195], v163 offset:51200
	ds_read_b128 v[196:199], v163 offset:52224
	ds_read_b128 v[200:203], v163 offset:53248
	ds_read_b128 v[204:207], v163 offset:54272
	ds_read_b128 v[208:211], v163 offset:55296
	ds_read_b128 v[212:215], v163 offset:56320
	global_load_lds_dwordx4 v[160:161], off
	s_add_i32 m0, s48, 0x2000
	s_add_u32 s46, s46, 0x40080
	v_lshl_add_u64 v[160:161], v[216:217], 0, s[14:15]
	s_addc_u32 s47, s47, 0
	s_add_i32 s48, s81, s50
	global_load_lds_dwordx4 v[160:161], off
	s_mov_b32 m0, s48
	v_lshl_add_u64 v[160:161], s[46:47], 0, v[144:145]
	global_load_lds_dwordx4 v[160:161], off
	s_add_i32 m0, s48, 0x2000
	v_lshl_add_u64 v[160:161], s[46:47], 0, v[148:149]
	global_load_lds_dwordx4 v[160:161], off
	s_mov_b32 m0, s66
	v_lshl_add_u64 v[160:161], v[218:219], 0, s[14:15]
	global_load_lds_dwordx4 v[160:161], off
	s_mov_b32 m0, s67
	v_lshl_add_u64 v[160:161], v[220:221], 0, s[14:15]
	global_load_lds_dwordx4 v[160:161], off
	s_waitcnt vmcnt(8)
	s_waitcnt lgkmcnt(0)
	s_barrier
	s_setprio 1
	s_waitcnt lgkmcnt(0)
	v_mfma_f32_16x16x32_bf16 v[62:65], v[130:133], v[184:187], v[62:65]
	v_mfma_f32_16x16x32_bf16 v[58:61], v[138:141], v[184:187], v[58:61]
	v_mfma_f32_16x16x32_bf16 v[54:57], v[130:133], v[192:195], v[54:57]
	v_mfma_f32_16x16x32_bf16 v[50:53], v[138:141], v[192:195], v[50:53]
	v_mfma_f32_16x16x32_bf16 v[46:49], v[130:133], v[200:203], v[46:49]
	v_mfma_f32_16x16x32_bf16 v[42:45], v[138:141], v[200:203], v[42:45]
	v_mfma_f32_16x16x32_bf16 v[38:41], v[130:133], v[208:211], v[38:41]
	v_mfma_f32_16x16x32_bf16 v[34:37], v[138:141], v[208:211], v[34:37]
	v_mfma_f32_16x16x32_bf16 v[62:65], v[134:137], v[188:191], v[62:65]
	v_mfma_f32_16x16x32_bf16 v[58:61], v[164:167], v[188:191], v[58:61]
	v_mfma_f32_16x16x32_bf16 v[54:57], v[134:137], v[196:199], v[54:57]
	v_mfma_f32_16x16x32_bf16 v[50:53], v[164:167], v[196:199], v[50:53]
	v_mfma_f32_16x16x32_bf16 v[46:49], v[134:137], v[204:207], v[46:49]
	v_mfma_f32_16x16x32_bf16 v[42:45], v[164:167], v[204:207], v[42:45]
	v_mfma_f32_16x16x32_bf16 v[38:41], v[134:137], v[212:215], v[38:41]
	v_mfma_f32_16x16x32_bf16 v[34:37], v[164:167], v[212:215], v[34:37]
	v_mfma_f32_16x16x32_bf16 v[30:33], v[168:171], v[184:187], v[30:33]
	v_mfma_f32_16x16x32_bf16 v[26:29], v[176:179], v[184:187], v[26:29]
	v_mfma_f32_16x16x32_bf16 v[22:25], v[168:171], v[192:195], v[22:25]
	v_mfma_f32_16x16x32_bf16 v[18:21], v[176:179], v[192:195], v[18:21]
	v_mfma_f32_16x16x32_bf16 v[14:17], v[168:171], v[200:203], v[14:17]
	v_mfma_f32_16x16x32_bf16 v[10:13], v[176:179], v[200:203], v[10:13]
	v_mfma_f32_16x16x32_bf16 v[6:9], v[168:171], v[208:211], v[6:9]
	v_mfma_f32_16x16x32_bf16 v[2:5], v[176:179], v[208:211], v[2:5]
	v_mfma_f32_16x16x32_bf16 v[30:33], v[172:175], v[188:191], v[30:33]
	v_mfma_f32_16x16x32_bf16 v[26:29], v[180:183], v[188:191], v[26:29]
	v_mfma_f32_16x16x32_bf16 v[22:25], v[172:175], v[196:199], v[22:25]
	v_mfma_f32_16x16x32_bf16 v[18:21], v[180:183], v[196:199], v[18:21]
	v_mfma_f32_16x16x32_bf16 v[14:17], v[172:175], v[204:207], v[14:17]
	v_mfma_f32_16x16x32_bf16 v[10:13], v[180:183], v[204:207], v[10:13]
	v_mfma_f32_16x16x32_bf16 v[6:9], v[172:175], v[212:215], v[6:9]
	v_mfma_f32_16x16x32_bf16 v[2:5], v[180:183], v[212:215], v[2:5]
	s_setprio 0
	s_barrier
	s_add_i32 s79, s79, 2
	s_add_u32 s44, s44, 0x100
	s_addc_u32 s45, s45, 0
	s_add_u32 s77, s77, 0x100
	s_addc_u32 s78, s78, 0
	s_cmp_gt_u32 s79, 13
	s_cbranch_scc0 .LBB0_1515
	s_and_b64 vcc, exec, s[16:17]
	s_cbranch_vccz .LBB0_1518
	s_barrier

; #define PG8_STAGE(bufoff, gbase, voff) do { _Pragma("unroll") for (int _i = 0; _i < 2; ++_i) \
;         __builtin_amdgcn_global_load_lds((const unsigned*)((const char*)(gbase) + (voff)[_i]), (PG8_LAS unsigned*)(lds + (bufoff) + ldsw + _i * 8192), 16, 0, 0); } while (0)
; #define PG8_LDA(dst, b, h) do { _Pragma("unroll") for (int m = 0; m < 4; ++m) _Pragma("unroll") for (int k = 0; k < 2; ++k) dst[m][k] = *(const PG8_LAS bf16x8*)(lds + PG8_SA(b, h) + aoff + m * 2048 + k * 1024); } while (0)
; #define PG8_LDB(dst, b, h) do { _Pragma("unroll") for (int n = 0; n < 2; ++n) _Pragma("unroll") for (int k = 0; k < 2; ++k) dst[n][k] = *(const PG8_LAS bf16x8*)(lds + PG8_SB(b, h) + boff + n * 2048 + k * 1024); } while (0)
; #define PG8_MMA(ai, bj, At, Bt) do { __builtin_amdgcn_s_setprio(1); _Pragma("unroll") for (int m = 0; m < 4; ++m) _Pragma("unroll") for (int n = 0; n < 2; ++n) _Pragma("unroll") for (int k = 0; k < 2; ++k) \
;         acc[ai][bj][m][n] = __builtin_amdgcn_mfma_f32_16x16x32_bf16(Bt[n][k], At[m][k], acc[ai][bj][m][n], 0, 0, 0); __builtin_amdgcn_s_setprio(0); } while (0)
; #define PG8_WAIT_V(n) asm volatile("s_waitcnt vmcnt(" #n ")" ::: "memory")
; #define PG8_WAIT_L(n) asm volatile("s_waitcnt lgkmcnt(" #n ")" ::: "memory")
; #define PG8_BAR __builtin_amdgcn_s_barrier()
; #define PG8_SCHED __builtin_amdgcn_sched_barrier(0)
; template <class Epi, class Sched, bool ALIGN_EPI = true>
; __device__ __forceinline__ void gemm_phase(PG8_LAS unsigned char* lds, const int K, const Sched& S, const Epi& E) {
;     ...
;             const bool last = (t == nt - 2);
;             const char* a1 = cA + (size_t)(t + 1) * kstep;
;             const char* a2 = last ? nA : cA + (size_t)(t + 2) * kstep; const char* b2 = last ? nB : cB + (size_t)(t + 2) * kstep;
;             const char* a3 = a2 + kstep; const char* b3 = b2 + kstep;
;             PG8_LDB(B0, 0, 0); PG8_LDB(B1, 0, 1); PG8_SCHED; PG8_LDA(At, 0, 0); PG8_STAGE(PG8_SA(1, 1), a1 + hstep, voffA);
;             PG8_WAIT_V(8); PG8_WAIT_L(0); PG8_BAR; PG8_MMA(0, 0, At, B0); PG8_MMA(0, 1, At, B1); PG8_BAR; PG8_SCHED;
;             PG8_LDA(At, 0, 1); PG8_STAGE(PG8_SB(0, 0), b2, voffB); PG8_STAGE(PG8_SB(0, 1), b2 + hstep, voffB); PG8_STAGE(PG8_SA(0, 0), a2, voffA);
;             PG8_WAIT_V(8); PG8_WAIT_L(0); PG8_BAR; PG8_MMA(1, 0, At, B0); PG8_MMA(1, 1, At, B1); PG8_BAR; PG8_SCHED;
.LBB0_1598:
	ds_read_b128 v[130:133], v181
	ds_read_b128 v[134:137], v181 offset:1024
	ds_read_b128 v[138:141], v181 offset:2048
	ds_read_b128 v[142:145], v181 offset:3072
	ds_read_b128 v[146:149], v182
	ds_read_b128 v[168:171], v182 offset:1024
	ds_read_b128 v[172:175], v182 offset:2048
	ds_read_b128 v[192:195], v182 offset:3072
	s_add_u32 s74, s72, 0xfffc0080
	s_addc_u32 s75, s73, -1
	s_cmp_eq_u32 s93, 12
	s_cselect_b32 s77, s13, s75
	s_cselect_b32 s76, s65, s74
	s_cselect_b32 s75, s63, s92
	s_cselect_b32 s74, s71, s91
	v_lshl_add_u64 v[176:177], s[72:73], 0, v[156:157]
	s_add_i32 m0, s57, 0xc000
	ds_read_b128 v[196:199], v183
	ds_read_b128 v[200:203], v183 offset:1024
	ds_read_b128 v[204:207], v183 offset:2048
	ds_read_b128 v[208:211], v183 offset:3072
	ds_read_b128 v[212:215], v183 offset:4096
	ds_read_b128 v[216:219], v183 offset:5120
	ds_read_b128 v[220:223], v183 offset:6144
	ds_read_b128 v[224:227], v183 offset:7168
	global_load_lds_dwordx4 v[176:177], off
	s_add_i32 m0, s57, 0xe000
	v_lshl_add_u64 v[176:177], s[72:73], 0, v[158:159]
	global_load_lds_dwordx4 v[176:177], off
	s_waitcnt vmcnt(8)
	s_waitcnt lgkmcnt(0)
	s_barrier
	s_setprio 1
	s_waitcnt lgkmcnt(0)
	v_mfma_f32_16x16x32_bf16 v[26:29], v[130:133], v[196:199], v[26:29]
	v_mfma_f32_16x16x32_bf16 v[14:17], v[138:141], v[196:199], v[14:17]
	v_mfma_f32_16x16x32_bf16 v[42:45], v[130:133], v[204:207], v[42:45]
	v_mfma_f32_16x16x32_bf16 v[30:33], v[138:141], v[204:207], v[30:33]
	v_mfma_f32_16x16x32_bf16 v[74:77], v[130:133], v[212:215], v[74:77]
	v_mfma_f32_16x16x32_bf16 v[46:49], v[138:141], v[212:215], v[46:49]
	v_mfma_f32_16x16x32_bf16 v[90:93], v[130:133], v[220:223], v[90:93]
	v_mfma_f32_16x16x32_bf16 v[78:81], v[138:141], v[220:223], v[78:81]
	v_mfma_f32_16x16x32_bf16 v[26:29], v[134:137], v[200:203], v[26:29]
	v_mfma_f32_16x16x32_bf16 v[14:17], v[142:145], v[200:203], v[14:17]
	v_mfma_f32_16x16x32_bf16 v[42:45], v[134:137], v[208:211], v[42:45]
	v_mfma_f32_16x16x32_bf16 v[30:33], v[142:145], v[208:211], v[30:33]
	v_mfma_f32_16x16x32_bf16 v[74:77], v[134:137], v[216:219], v[74:77]
	v_mfma_f32_16x16x32_bf16 v[46:49], v[142:145], v[216:219], v[46:49]
	v_mfma_f32_16x16x32_bf16 v[90:93], v[134:137], v[224:227], v[90:93]
	v_mfma_f32_16x16x32_bf16 v[78:81], v[142:145], v[224:227], v[78:81]
	v_mfma_f32_16x16x32_bf16 v[6:9], v[146:149], v[196:199], v[6:9]
	v_mfma_f32_16x16x32_bf16 v[2:5], v[172:175], v[196:199], v[2:5]
	v_mfma_f32_16x16x32_bf16 v[18:21], v[146:149], v[204:207], v[18:21]
	v_mfma_f32_16x16x32_bf16 v[10:13], v[172:175], v[204:207], v[10:13]
	v_mfma_f32_16x16x32_bf16 v[34:37], v[146:149], v[212:215], v[34:37]
	v_mfma_f32_16x16x32_bf16 v[22:25], v[172:175], v[212:215], v[22:25]
	v_mfma_f32_16x16x32_bf16 v[50:53], v[146:149], v[220:223], v[50:53]
	v_mfma_f32_16x16x32_bf16 v[38:41], v[172:175], v[220:223], v[38:41]
	v_mfma_f32_16x16x32_bf16 v[6:9], v[168:171], v[200:203], v[6:9]
	v_mfma_f32_16x16x32_bf16 v[2:5], v[192:195], v[200:203], v[2:5]
	v_mfma_f32_16x16x32_bf16 v[18:21], v[168:171], v[208:211], v[18:21]
	v_mfma_f32_16x16x32_bf16 v[10:13], v[192:195], v[208:211], v[10:13]
	v_mfma_f32_16x16x32_bf16 v[34:37], v[168:171], v[216:219], v[34:37]
	v_mfma_f32_16x16x32_bf16 v[22:25], v[192:195], v[216:219], v[22:25]
	v_mfma_f32_16x16x32_bf16 v[50:53], v[168:171], v[224:227], v[50:53]
	v_mfma_f32_16x16x32_bf16 v[38:41], v[192:195], v[224:227], v[38:41]
	s_setprio 0
	s_barrier
	s_add_i32 s94, s86, s56
	v_lshl_add_u64 v[176:177], s[74:75], 0, v[150:151]
	s_mov_b32 m0, s94
	ds_read_b128 v[196:199], v183 offset:16384
	ds_read_b128 v[200:203], v183 offset:17408
	ds_read_b128 v[204:207], v183 offset:18432
	ds_read_b128 v[208:211], v183 offset:19456
	ds_read_b128 v[212:215], v183 offset:20480
	ds_read_b128 v[216:219], v183 offset:21504
	ds_read_b128 v[220:223], v183 offset:22528
	ds_read_b128 v[224:227], v183 offset:23552
	global_load_lds_dwordx4 v[176:177], off
	s_add_i32 m0, s94, 0x2000
	s_add_u32 s94, s74, 0x40000
	v_lshl_add_u64 v[228:229], s[74:75], 0, v[152:153]
	s_addc_u32 s95, s75, 0
	s_add_i32 s96, s87, s56
	global_load_lds_dwordx4 v[228:229], off
	v_lshl_add_u64 v[230:231], s[94:95], 0, v[150:151]
	s_mov_b32 m0, s96
	v_lshl_add_u64 v[232:233], s[76:77], 0, v[152:153]
	global_load_lds_dwordx4 v[230:231], off
	s_add_i32 m0, s96, 0x2000
	v_lshl_add_u64 v[230:231], s[94:95], 0, v[152:153]
	global_load_lds_dwordx4 v[230:231], off
	s_mov_b32 m0, s57
	v_lshl_add_u64 v[230:231], s[76:77], 0, v[150:151]
	global_load_lds_dwordx4 v[230:231], off
	s_mov_b32 m0, s58
	s_nop 0
	global_load_lds_dwordx4 v[232:233], off
	s_waitcnt vmcnt(8)
	s_waitcnt lgkmcnt(0)
	s_barrier
; #define PG8_STAGE(bufoff, gbase, voff) do { _Pragma("unroll") for (int _i = 0; _i < 2; ++_i) \
;         __builtin_amdgcn_global_load_lds((const unsigned*)((const char*)(gbase) + (voff)[_i]), (PG8_LAS unsigned*)(lds + (bufoff) + ldsw + _i * 8192), 16, 0, 0); } while (0)
; #define PG8_LDA(dst, b, h) do { _Pragma("unroll") for (int m = 0; m < 4; ++m) _Pragma("unroll") for (int k = 0; k < 2; ++k) dst[m][k] = *(const PG8_LAS bf16x8*)(lds + PG8_SA(b, h) + aoff + m * 2048 + k * 1024); } while (0)
; #define PG8_LDB(dst, b, h) do { _Pragma("unroll") for (int n = 0; n < 2; ++n) _Pragma("unroll") for (int k = 0; k < 2; ++k) dst[n][k] = *(const PG8_LAS bf16x8*)(lds + PG8_SB(b, h) + boff + n * 2048 + k * 1024); } while (0)
; #define PG8_MMA(ai, bj, At, Bt) do { __builtin_amdgcn_s_setprio(1); _Pragma("unroll") for (int m = 0; m < 4; ++m) _Pragma("unroll") for (int n = 0; n < 2; ++n) _Pragma("unroll") for (int k = 0; k < 2; ++k) \
;         acc[ai][bj][m][n] = __builtin_amdgcn_mfma_f32_16x16x32_bf16(Bt[n][k], At[m][k], acc[ai][bj][m][n], 0, 0, 0); __builtin_amdgcn_s_setprio(0); } while (0)
; #define PG8_WAIT_V(n) asm volatile("s_waitcnt vmcnt(" #n ")" ::: "memory")
; #define PG8_WAIT_L(n) asm volatile("s_waitcnt lgkmcnt(" #n ")" ::: "memory")
; #define PG8_BAR __builtin_amdgcn_s_barrier()
; #define PG8_SCHED __builtin_amdgcn_sched_barrier(0)
; template <class Epi, class Sched, bool ALIGN_EPI = true>
; __device__ __forceinline__ void gemm_phase(PG8_LAS unsigned char* lds, const int K, const Sched& S, const Epi& E) {
;     ...
;             PG8_WAIT_V(8); PG8_WAIT_L(0); PG8_BAR; PG8_MMA(1, 0, At, B0); PG8_MMA(1, 1, At, B1); PG8_BAR; PG8_SCHED;
;             PG8_LDB(B0, 1, 0); PG8_LDB(B1, 1, 1); PG8_SCHED; PG8_LDA(At, 1, 0); PG8_STAGE(PG8_SA(0, 1), a2 + hstep, voffA);
;             PG8_WAIT_V(8); PG8_WAIT_L(0); PG8_BAR; PG8_MMA(0, 0, At, B0); PG8_MMA(0, 1, At, B1); PG8_BAR; PG8_SCHED;
	s_setprio 1
	s_waitcnt lgkmcnt(0)
	v_mfma_f32_16x16x32_bf16 v[122:125], v[130:133], v[196:199], v[122:125]
	v_mfma_f32_16x16x32_bf16 v[94:97], v[138:141], v[196:199], v[94:97]
	v_mfma_f32_16x16x32_bf16 v[126:129], v[130:133], v[204:207], v[126:129]
	v_mfma_f32_16x16x32_bf16 v[118:121], v[138:141], v[204:207], v[118:121]
	v_mfma_f32_16x16x32_bf16 v[114:117], v[130:133], v[212:215], v[114:117]
	v_mfma_f32_16x16x32_bf16 v[110:113], v[138:141], v[212:215], v[110:113]
	v_mfma_f32_16x16x32_bf16 v[70:73], v[130:133], v[220:223], v[70:73]
	v_mfma_f32_16x16x32_bf16 v[66:69], v[138:141], v[220:223], v[66:69]
	v_mfma_f32_16x16x32_bf16 v[122:125], v[134:137], v[200:203], v[122:125]
	v_mfma_f32_16x16x32_bf16 v[94:97], v[142:145], v[200:203], v[94:97]
	v_mfma_f32_16x16x32_bf16 v[126:129], v[134:137], v[208:211], v[126:129]
	v_mfma_f32_16x16x32_bf16 v[118:121], v[142:145], v[208:211], v[118:121]
	v_mfma_f32_16x16x32_bf16 v[114:117], v[134:137], v[216:219], v[114:117]
	v_mfma_f32_16x16x32_bf16 v[110:113], v[142:145], v[216:219], v[110:113]
	v_mfma_f32_16x16x32_bf16 v[70:73], v[134:137], v[224:227], v[70:73]
	v_mfma_f32_16x16x32_bf16 v[66:69], v[142:145], v[224:227], v[66:69]
	v_mfma_f32_16x16x32_bf16 v[82:85], v[146:149], v[196:199], v[82:85]
	v_mfma_f32_16x16x32_bf16 v[54:57], v[172:175], v[196:199], v[54:57]
	v_mfma_f32_16x16x32_bf16 v[102:105], v[146:149], v[204:207], v[102:105]
	v_mfma_f32_16x16x32_bf16 v[86:89], v[172:175], v[204:207], v[86:89]
	v_mfma_f32_16x16x32_bf16 v[106:109], v[146:149], v[212:215], v[106:109]
	v_mfma_f32_16x16x32_bf16 v[98:101], v[172:175], v[212:215], v[98:101]
	v_mfma_f32_16x16x32_bf16 v[62:65], v[146:149], v[220:223], v[62:65]
	v_mfma_f32_16x16x32_bf16 v[58:61], v[172:175], v[220:223], v[58:61]
	v_mfma_f32_16x16x32_bf16 v[82:85], v[168:171], v[200:203], v[82:85]
	v_mfma_f32_16x16x32_bf16 v[54:57], v[192:195], v[200:203], v[54:57]
	v_mfma_f32_16x16x32_bf16 v[102:105], v[168:171], v[208:211], v[102:105]
	v_mfma_f32_16x16x32_bf16 v[86:89], v[192:195], v[208:211], v[86:89]
	v_mfma_f32_16x16x32_bf16 v[106:109], v[168:171], v[216:219], v[106:109]
	v_mfma_f32_16x16x32_bf16 v[98:101], v[192:195], v[216:219], v[98:101]
	v_mfma_f32_16x16x32_bf16 v[62:65], v[168:171], v[224:227], v[62:65]
	v_mfma_f32_16x16x32_bf16 v[58:61], v[192:195], v[224:227], v[58:61]
	s_setprio 0
	s_barrier
	s_add_i32 s94, 0, 0x18000
	s_add_i32 s95, 0, 0x1c000
	v_add_u32_e32 v142, s94, v1
	v_add_u32_e32 v191, s95, v1
	ds_read_b128 v[130:133], v142
	ds_read_b128 v[134:137], v142 offset:1024
	ds_read_b128 v[138:141], v142 offset:2048
	ds_read_b128 v[142:145], v142 offset:3072
	ds_read_b128 v[146:149], v191
	ds_read_b128 v[168:171], v191 offset:1024
	ds_read_b128 v[172:175], v191 offset:2048
	ds_read_b128 v[192:195], v191 offset:3072
	s_add_u32 s76, s76, 0x40000
	s_addc_u32 s77, s77, 0
	s_mov_b32 m0, s59
	v_lshl_add_u64 v[234:235], s[76:77], 0, v[150:151]
	ds_read_b128 v[196:199], v183 offset:32768
	ds_read_b128 v[200:203], v183 offset:33792
	ds_read_b128 v[204:207], v183 offset:34816
	ds_read_b128 v[208:211], v183 offset:35840
	ds_read_b128 v[212:215], v183 offset:36864
	ds_read_b128 v[216:219], v183 offset:37888
	ds_read_b128 v[220:223], v183 offset:38912
	ds_read_b128 v[224:227], v183 offset:39936
	global_load_lds_dwordx4 v[234:235], off
	s_mov_b32 m0, s78
	v_lshl_add_u64 v[234:235], s[76:77], 0, v[152:153]
	global_load_lds_dwordx4 v[234:235], off
	s_waitcnt vmcnt(8)
	s_waitcnt lgkmcnt(0)
	s_barrier
	s_setprio 1
	s_waitcnt lgkmcnt(0)
	v_mfma_f32_16x16x32_bf16 v[26:29], v[130:133], v[196:199], v[26:29]
	v_mfma_f32_16x16x32_bf16 v[14:17], v[138:141], v[196:199], v[14:17]
	v_mfma_f32_16x16x32_bf16 v[42:45], v[130:133], v[204:207], v[42:45]
	v_mfma_f32_16x16x32_bf16 v[30:33], v[138:141], v[204:207], v[30:33]
	v_mfma_f32_16x16x32_bf16 v[74:77], v[130:133], v[212:215], v[74:77]
	v_mfma_f32_16x16x32_bf16 v[46:49], v[138:141], v[212:215], v[46:49]
	v_mfma_f32_16x16x32_bf16 v[90:93], v[130:133], v[220:223], v[90:93]
	v_mfma_f32_16x16x32_bf16 v[78:81], v[138:141], v[220:223], v[78:81]
	v_mfma_f32_16x16x32_bf16 v[26:29], v[134:137], v[200:203], v[26:29]
	v_mfma_f32_16x16x32_bf16 v[14:17], v[142:145], v[200:203], v[14:17]
	v_mfma_f32_16x16x32_bf16 v[42:45], v[134:137], v[208:211], v[42:45]
	v_mfma_f32_16x16x32_bf16 v[30:33], v[142:145], v[208:211], v[30:33]
	v_mfma_f32_16x16x32_bf16 v[74:77], v[134:137], v[216:219], v[74:77]
	v_mfma_f32_16x16x32_bf16 v[46:49], v[142:145], v[216:219], v[46:49]
	v_mfma_f32_16x16x32_bf16 v[90:93], v[134:137], v[224:227], v[90:93]
	v_mfma_f32_16x16x32_bf16 v[78:81], v[142:145], v[224:227], v[78:81]
	v_mfma_f32_16x16x32_bf16 v[6:9], v[146:149], v[196:199], v[6:9]
	v_mfma_f32_16x16x32_bf16 v[2:5], v[172:175], v[196:199], v[2:5]
	v_mfma_f32_16x16x32_bf16 v[18:21], v[146:149], v[204:207], v[18:21]
	v_mfma_f32_16x16x32_bf16 v[10:13], v[172:175], v[204:207], v[10:13]
	v_mfma_f32_16x16x32_bf16 v[34:37], v[146:149], v[212:215], v[34:37]
	v_mfma_f32_16x16x32_bf16 v[22:25], v[172:175], v[212:215], v[22:25]
	v_mfma_f32_16x16x32_bf16 v[50:53], v[146:149], v[220:223], v[50:53]
	v_mfma_f32_16x16x32_bf16 v[38:41], v[172:175], v[220:223], v[38:41]
	v_mfma_f32_16x16x32_bf16 v[6:9], v[168:171], v[200:203], v[6:9]
	v_mfma_f32_16x16x32_bf16 v[2:5], v[192:195], v[200:203], v[2:5]
	v_mfma_f32_16x16x32_bf16 v[18:21], v[168:171], v[208:211], v[18:21]
	v_mfma_f32_16x16x32_bf16 v[10:13], v[192:195], v[208:211], v[10:13]
	v_mfma_f32_16x16x32_bf16 v[34:37], v[168:171], v[216:219], v[34:37]
	v_mfma_f32_16x16x32_bf16 v[22:25], v[192:195], v[216:219], v[22:25]
	v_mfma_f32_16x16x32_bf16 v[50:53], v[168:171], v[224:227], v[50:53]
	v_mfma_f32_16x16x32_bf16 v[38:41], v[192:195], v[224:227], v[38:41]
	s_setprio 0
	s_barrier
; #define PG8_STAGE(bufoff, gbase, voff) do { _Pragma("unroll") for (int _i = 0; _i < 2; ++_i) \
;         __builtin_amdgcn_global_load_lds((const unsigned*)((const char*)(gbase) + (voff)[_i]), (PG8_LAS unsigned*)(lds + (bufoff) + ldsw + _i * 8192), 16, 0, 0); } while (0)
; #define PG8_LDA(dst, b, h) do { _Pragma("unroll") for (int m = 0; m < 4; ++m) _Pragma("unroll") for (int k = 0; k < 2; ++k) dst[m][k] = *(const PG8_LAS bf16x8*)(lds + PG8_SA(b, h) + aoff + m * 2048 + k * 1024); } while (0)
; #define PG8_MMA(ai, bj, At, Bt) do { __builtin_amdgcn_s_setprio(1); _Pragma("unroll") for (int m = 0; m < 4; ++m) _Pragma("unroll") for (int n = 0; n < 2; ++n) _Pragma("unroll") for (int k = 0; k < 2; ++k) \
;         acc[ai][bj][m][n] = __builtin_amdgcn_mfma_f32_16x16x32_bf16(Bt[n][k], At[m][k], acc[ai][bj][m][n], 0, 0, 0); __builtin_amdgcn_s_setprio(0); } while (0)
; #define PG8_WAIT_V(n) asm volatile("s_waitcnt vmcnt(" #n ")" ::: "memory")
; #define PG8_WAIT_L(n) asm volatile("s_waitcnt lgkmcnt(" #n ")" ::: "memory")
; #define PG8_BAR __builtin_amdgcn_s_barrier()
; #define PG8_SCHED __builtin_amdgcn_sched_barrier(0)
; template <class Epi, class Sched, bool ALIGN_EPI = true>
; __device__ __forceinline__ void gemm_phase(PG8_LAS unsigned char* lds, const int K, const Sched& S, const Epi& E) {
;     ...
;             PG8_LDA(At, 1, 1); PG8_STAGE(PG8_SB(1, 0), b3, voffB); PG8_STAGE(PG8_SB(1, 1), b3 + hstep, voffB); PG8_STAGE(PG8_SA(1, 0), a3, voffA);
;             PG8_WAIT_V(8); PG8_WAIT_L(0); PG8_BAR; PG8_MMA(1, 0, At, B0); PG8_MMA(1, 1, At, B1); PG8_BAR; PG8_SCHED;
;         }
;         if constexpr (Epi::TOUCH) asm volatile("" :: "v"(td));
;         if constexpr (ALIGN_EPI) { if (wr == 0) PG8_BAR; }
	s_add_i32 s76, s94, s56
	v_lshl_add_u64 v[176:177], v[176:177], 0, s[24:25]
	s_mov_b32 m0, s76
	ds_read_b128 v[196:199], v183 offset:49152
	ds_read_b128 v[200:203], v183 offset:50176
	ds_read_b128 v[204:207], v183 offset:51200
	ds_read_b128 v[208:211], v183 offset:52224
	ds_read_b128 v[212:215], v183 offset:53248
	ds_read_b128 v[216:219], v183 offset:54272
	ds_read_b128 v[220:223], v183 offset:55296
	ds_read_b128 v[224:227], v183 offset:56320
	global_load_lds_dwordx4 v[176:177], off
	s_add_i32 m0, s76, 0x2000
	s_add_u32 s74, s74, 0x40080
	v_lshl_add_u64 v[176:177], v[228:229], 0, s[24:25]
	s_addc_u32 s75, s75, 0
	s_add_i32 s76, s95, s56
	global_load_lds_dwordx4 v[176:177], off
	s_mov_b32 m0, s76
	v_lshl_add_u64 v[176:177], s[74:75], 0, v[150:151]
	global_load_lds_dwordx4 v[176:177], off
	s_add_i32 m0, s76, 0x2000
	v_lshl_add_u64 v[176:177], s[74:75], 0, v[152:153]
	global_load_lds_dwordx4 v[176:177], off
	s_mov_b32 m0, s82
	v_lshl_add_u64 v[176:177], v[230:231], 0, s[24:25]
	global_load_lds_dwordx4 v[176:177], off
	s_mov_b32 m0, s83
	v_lshl_add_u64 v[176:177], v[232:233], 0, s[24:25]
	global_load_lds_dwordx4 v[176:177], off
	s_waitcnt vmcnt(8)
	s_waitcnt lgkmcnt(0)
	s_barrier
	s_setprio 1
	s_waitcnt lgkmcnt(0)
	v_mfma_f32_16x16x32_bf16 v[122:125], v[130:133], v[196:199], v[122:125]
	v_mfma_f32_16x16x32_bf16 v[94:97], v[138:141], v[196:199], v[94:97]
	v_mfma_f32_16x16x32_bf16 v[126:129], v[130:133], v[204:207], v[126:129]
	v_mfma_f32_16x16x32_bf16 v[118:121], v[138:141], v[204:207], v[118:121]
	v_mfma_f32_16x16x32_bf16 v[114:117], v[130:133], v[212:215], v[114:117]
	v_mfma_f32_16x16x32_bf16 v[110:113], v[138:141], v[212:215], v[110:113]
	v_mfma_f32_16x16x32_bf16 v[70:73], v[130:133], v[220:223], v[70:73]
	v_mfma_f32_16x16x32_bf16 v[66:69], v[138:141], v[220:223], v[66:69]
	v_mfma_f32_16x16x32_bf16 v[122:125], v[134:137], v[200:203], v[122:125]
	v_mfma_f32_16x16x32_bf16 v[94:97], v[142:145], v[200:203], v[94:97]
	v_mfma_f32_16x16x32_bf16 v[126:129], v[134:137], v[208:211], v[126:129]
	v_mfma_f32_16x16x32_bf16 v[118:121], v[142:145], v[208:211], v[118:121]
	v_mfma_f32_16x16x32_bf16 v[114:117], v[134:137], v[216:219], v[114:117]
	v_mfma_f32_16x16x32_bf16 v[110:113], v[142:145], v[216:219], v[110:113]
	v_mfma_f32_16x16x32_bf16 v[70:73], v[134:137], v[224:227], v[70:73]
	v_mfma_f32_16x16x32_bf16 v[66:69], v[142:145], v[224:227], v[66:69]
	v_mfma_f32_16x16x32_bf16 v[82:85], v[146:149], v[196:199], v[82:85]
	v_mfma_f32_16x16x32_bf16 v[54:57], v[172:175], v[196:199], v[54:57]
	v_mfma_f32_16x16x32_bf16 v[102:105], v[146:149], v[204:207], v[102:105]
	v_mfma_f32_16x16x32_bf16 v[86:89], v[172:175], v[204:207], v[86:89]
	v_mfma_f32_16x16x32_bf16 v[106:109], v[146:149], v[212:215], v[106:109]
	v_mfma_f32_16x16x32_bf16 v[98:101], v[172:175], v[212:215], v[98:101]
	v_mfma_f32_16x16x32_bf16 v[62:65], v[146:149], v[220:223], v[62:65]
	v_mfma_f32_16x16x32_bf16 v[58:61], v[172:175], v[220:223], v[58:61]
	v_mfma_f32_16x16x32_bf16 v[82:85], v[168:171], v[200:203], v[82:85]
	v_mfma_f32_16x16x32_bf16 v[54:57], v[192:195], v[200:203], v[54:57]
	v_mfma_f32_16x16x32_bf16 v[102:105], v[168:171], v[208:211], v[102:105]
	v_mfma_f32_16x16x32_bf16 v[86:89], v[192:195], v[208:211], v[86:89]
	v_mfma_f32_16x16x32_bf16 v[106:109], v[168:171], v[216:219], v[106:109]
	v_mfma_f32_16x16x32_bf16 v[98:101], v[192:195], v[216:219], v[98:101]
	v_mfma_f32_16x16x32_bf16 v[62:65], v[168:171], v[224:227], v[62:65]
	v_mfma_f32_16x16x32_bf16 v[58:61], v[192:195], v[224:227], v[58:61]
	s_setprio 0
	s_barrier
	s_add_i32 s93, s93, 2
	s_add_u32 s72, s72, 0x100
	s_addc_u32 s73, s73, 0
	s_add_u32 s91, s91, 0x100
	s_addc_u32 s92, s92, 0
	s_cmp_gt_u32 s93, 13
	s_cbranch_scc0 .LBB0_1598
	s_and_b64 vcc, exec, s[36:37]
	s_cbranch_vccz .LBB0_1601
	s_barrier

; #define PG8_STAGE(bufoff, gbase, voff) do { _Pragma("unroll") for (int _i = 0; _i < 2; ++_i) \
;         __builtin_amdgcn_global_load_lds((const unsigned*)((const char*)(gbase) + (voff)[_i]), (PG8_LAS unsigned*)(lds + (bufoff) + ldsw + _i * 8192), 16, 0, 0); } while (0)
; #define PG8_LDA(dst, b, h) do { _Pragma("unroll") for (int m = 0; m < 4; ++m) _Pragma("unroll") for (int k = 0; k < 2; ++k) dst[m][k] = *(const PG8_LAS bf16x8*)(lds + PG8_SA(b, h) + aoff + m * 2048 + k * 1024); } while (0)
; #define PG8_LDB(dst, b, h) do { _Pragma("unroll") for (int n = 0; n < 2; ++n) _Pragma("unroll") for (int k = 0; k < 2; ++k) dst[n][k] = *(const PG8_LAS bf16x8*)(lds + PG8_SB(b, h) + boff + n * 2048 + k * 1024); } while (0)
; #define PG8_MMA(ai, bj, At, Bt) do { __builtin_amdgcn_s_setprio(1); _Pragma("unroll") for (int m = 0; m < 4; ++m) _Pragma("unroll") for (int n = 0; n < 2; ++n) _Pragma("unroll") for (int k = 0; k < 2; ++k) \
;         acc[ai][bj][m][n] = __builtin_amdgcn_mfma_f32_16x16x32_bf16(Bt[n][k], At[m][k], acc[ai][bj][m][n], 0, 0, 0); __builtin_amdgcn_s_setprio(0); } while (0)
; #define PG8_WAIT_V(n) asm volatile("s_waitcnt vmcnt(" #n ")" ::: "memory")
; #define PG8_WAIT_L(n) asm volatile("s_waitcnt lgkmcnt(" #n ")" ::: "memory")
; #define PG8_BAR __builtin_amdgcn_s_barrier()
; #define PG8_SCHED __builtin_amdgcn_sched_barrier(0)
; template <class Epi, class Sched, bool ALIGN_EPI = true>
; __device__ __forceinline__ void gemm_phase(PG8_LAS unsigned char* lds, const int K, const Sched& S, const Epi& E) {
;     ...
;         for (int t = 0; t < nt; t += 2) {
;             const bool last = (t == nt - 2);
;             const char* a1 = cA + (size_t)(t + 1) * kstep;
;             const char* a2 = last ? nA : cA + (size_t)(t + 2) * kstep; const char* b2 = last ? nB : cB + (size_t)(t + 2) * kstep;
;             const char* a3 = a2 + kstep; const char* b3 = b2 + kstep;
;             PG8_LDB(B0, 0, 0); PG8_LDB(B1, 0, 1); PG8_SCHED; PG8_LDA(At, 0, 0); PG8_STAGE(PG8_SA(1, 1), a1 + hstep, voffA);
;             PG8_WAIT_V(8); PG8_WAIT_L(0); PG8_BAR; PG8_MMA(0, 0, At, B0); PG8_MMA(0, 1, At, B1); PG8_BAR; PG8_SCHED;
;             PG8_LDA(At, 0, 1); PG8_STAGE(PG8_SB(0, 0), b2, voffB); PG8_STAGE(PG8_SB(0, 1), b2 + hstep, voffB); PG8_STAGE(PG8_SA(0, 0), a2, voffA);
;             PG8_WAIT_V(8); PG8_WAIT_L(0); PG8_BAR; PG8_MMA(1, 0, At, B0); PG8_MMA(1, 1, At, B1); PG8_BAR; PG8_SCHED;
.LBB0_1713:
	ds_read_b128 v[156:159], v152
	ds_read_b128 v[164:167], v152 offset:1024
	ds_read_b128 v[168:171], v152 offset:2048
	ds_read_b128 v[172:175], v152 offset:3072
	ds_read_b128 v[176:179], v153
	ds_read_b128 v[180:183], v153 offset:1024
	ds_read_b128 v[184:187], v153 offset:2048
	ds_read_b128 v[188:191], v153 offset:3072
	s_add_u32 s38, s36, 0xfffc0080
	s_addc_u32 s39, s37, -1
	s_cmp_eq_u32 s68, 12
	s_cselect_b32 s41, s17, s39
	s_cselect_b32 s40, s23, s38
	s_cselect_b32 s39, s15, s67
	s_cselect_b32 s38, s25, s66
	v_lshl_add_u64 v[150:151], s[36:37], 0, v[142:143]
	s_add_i32 m0, s45, 0xc000
	ds_read_b128 v[192:195], v154
	ds_read_b128 v[196:199], v154 offset:1024
	ds_read_b128 v[200:203], v154 offset:2048
	ds_read_b128 v[204:207], v154 offset:3072
	ds_read_b128 v[208:211], v154 offset:4096
	ds_read_b128 v[212:215], v154 offset:5120
	ds_read_b128 v[216:219], v154 offset:6144
	ds_read_b128 v[220:223], v154 offset:7168
	global_load_lds_dwordx4 v[150:151], off
	s_add_i32 m0, s45, 0xe000
	v_lshl_add_u64 v[150:151], s[36:37], 0, v[144:145]
	global_load_lds_dwordx4 v[150:151], off
	s_waitcnt vmcnt(8)
	s_waitcnt lgkmcnt(0)
	s_barrier
	s_setprio 1
	s_waitcnt lgkmcnt(0)
	v_mfma_f32_16x16x32_bf16 v[126:129], v[156:159], v[192:195], v[126:129]
	v_mfma_f32_16x16x32_bf16 v[122:125], v[168:171], v[192:195], v[122:125]
	v_mfma_f32_16x16x32_bf16 v[114:117], v[156:159], v[200:203], v[114:117]
	v_mfma_f32_16x16x32_bf16 v[106:109], v[168:171], v[200:203], v[106:109]
	v_mfma_f32_16x16x32_bf16 v[98:101], v[156:159], v[208:211], v[98:101]
	v_mfma_f32_16x16x32_bf16 v[90:93], v[168:171], v[208:211], v[90:93]
	v_mfma_f32_16x16x32_bf16 v[82:85], v[156:159], v[216:219], v[82:85]
	v_mfma_f32_16x16x32_bf16 v[74:77], v[168:171], v[216:219], v[74:77]
	v_mfma_f32_16x16x32_bf16 v[126:129], v[164:167], v[196:199], v[126:129]
	v_mfma_f32_16x16x32_bf16 v[122:125], v[172:175], v[196:199], v[122:125]
	v_mfma_f32_16x16x32_bf16 v[114:117], v[164:167], v[204:207], v[114:117]
	v_mfma_f32_16x16x32_bf16 v[106:109], v[172:175], v[204:207], v[106:109]
	v_mfma_f32_16x16x32_bf16 v[98:101], v[164:167], v[212:215], v[98:101]
	v_mfma_f32_16x16x32_bf16 v[90:93], v[172:175], v[212:215], v[90:93]
	v_mfma_f32_16x16x32_bf16 v[82:85], v[164:167], v[220:223], v[82:85]
	v_mfma_f32_16x16x32_bf16 v[74:77], v[172:175], v[220:223], v[74:77]
	v_mfma_f32_16x16x32_bf16 v[118:121], v[176:179], v[192:195], v[118:121]
	v_mfma_f32_16x16x32_bf16 v[110:113], v[184:187], v[192:195], v[110:113]
	v_mfma_f32_16x16x32_bf16 v[102:105], v[176:179], v[200:203], v[102:105]
	v_mfma_f32_16x16x32_bf16 v[94:97], v[184:187], v[200:203], v[94:97]
	v_mfma_f32_16x16x32_bf16 v[86:89], v[176:179], v[208:211], v[86:89]
	v_mfma_f32_16x16x32_bf16 v[78:81], v[184:187], v[208:211], v[78:81]
	v_mfma_f32_16x16x32_bf16 v[70:73], v[176:179], v[216:219], v[70:73]
	v_mfma_f32_16x16x32_bf16 v[66:69], v[184:187], v[216:219], v[66:69]
	v_mfma_f32_16x16x32_bf16 v[118:121], v[180:183], v[196:199], v[118:121]
	v_mfma_f32_16x16x32_bf16 v[110:113], v[188:191], v[196:199], v[110:113]
	v_mfma_f32_16x16x32_bf16 v[102:105], v[180:183], v[204:207], v[102:105]
	v_mfma_f32_16x16x32_bf16 v[94:97], v[188:191], v[204:207], v[94:97]
	v_mfma_f32_16x16x32_bf16 v[86:89], v[180:183], v[212:215], v[86:89]
	v_mfma_f32_16x16x32_bf16 v[78:81], v[188:191], v[212:215], v[78:81]
	v_mfma_f32_16x16x32_bf16 v[70:73], v[180:183], v[220:223], v[70:73]
	v_mfma_f32_16x16x32_bf16 v[66:69], v[188:191], v[220:223], v[66:69]
	s_setprio 0
	s_barrier
	s_add_i32 s69, s56, s44
	v_lshl_add_u64 v[150:151], s[38:39], 0, v[132:133]
	s_mov_b32 m0, s69
	ds_read_b128 v[192:195], v154 offset:16384
	ds_read_b128 v[196:199], v154 offset:17408
	ds_read_b128 v[200:203], v154 offset:18432
	ds_read_b128 v[204:207], v154 offset:19456
	ds_read_b128 v[208:211], v154 offset:20480
	ds_read_b128 v[212:215], v154 offset:21504
	ds_read_b128 v[216:219], v154 offset:22528
	ds_read_b128 v[220:223], v154 offset:23552
	global_load_lds_dwordx4 v[150:151], off
	s_add_i32 m0, s69, 0x2000
	s_add_u32 s70, s38, 0x40000
	v_lshl_add_u64 v[160:161], s[38:39], 0, v[136:137]
	s_addc_u32 s71, s39, 0
	s_add_i32 s69, s57, s44
	global_load_lds_dwordx4 v[160:161], off
	v_lshl_add_u64 v[224:225], s[70:71], 0, v[132:133]
	s_mov_b32 m0, s69
	v_lshl_add_u64 v[226:227], s[40:41], 0, v[134:135]
	global_load_lds_dwordx4 v[224:225], off
	s_add_i32 m0, s69, 0x2000
	v_lshl_add_u64 v[224:225], s[70:71], 0, v[136:137]
	global_load_lds_dwordx4 v[224:225], off
	s_mov_b32 m0, s45
	v_lshl_add_u64 v[224:225], s[40:41], 0, v[130:131]
	global_load_lds_dwordx4 v[224:225], off
	s_mov_b32 m0, s46
	s_nop 0
	global_load_lds_dwordx4 v[226:227], off
	s_waitcnt vmcnt(8)
	s_waitcnt lgkmcnt(0)
	s_barrier
; #define PG8_STAGE(bufoff, gbase, voff) do { _Pragma("unroll") for (int _i = 0; _i < 2; ++_i) \
;         __builtin_amdgcn_global_load_lds((const unsigned*)((const char*)(gbase) + (voff)[_i]), (PG8_LAS unsigned*)(lds + (bufoff) + ldsw + _i * 8192), 16, 0, 0); } while (0)
; #define PG8_LDA(dst, b, h) do { _Pragma("unroll") for (int m = 0; m < 4; ++m) _Pragma("unroll") for (int k = 0; k < 2; ++k) dst[m][k] = *(const PG8_LAS bf16x8*)(lds + PG8_SA(b, h) + aoff + m * 2048 + k * 1024); } while (0)
; #define PG8_LDB(dst, b, h) do { _Pragma("unroll") for (int n = 0; n < 2; ++n) _Pragma("unroll") for (int k = 0; k < 2; ++k) dst[n][k] = *(const PG8_LAS bf16x8*)(lds + PG8_SB(b, h) + boff + n * 2048 + k * 1024); } while (0)
; #define PG8_MMA(ai, bj, At, Bt) do { __builtin_amdgcn_s_setprio(1); _Pragma("unroll") for (int m = 0; m < 4; ++m) _Pragma("unroll") for (int n = 0; n < 2; ++n) _Pragma("unroll") for (int k = 0; k < 2; ++k) \
;         acc[ai][bj][m][n] = __builtin_amdgcn_mfma_f32_16x16x32_bf16(Bt[n][k], At[m][k], acc[ai][bj][m][n], 0, 0, 0); __builtin_amdgcn_s_setprio(0); } while (0)
; #define PG8_WAIT_V(n) asm volatile("s_waitcnt vmcnt(" #n ")" ::: "memory")
; #define PG8_WAIT_L(n) asm volatile("s_waitcnt lgkmcnt(" #n ")" ::: "memory")
; #define PG8_BAR __builtin_amdgcn_s_barrier()
; #define PG8_SCHED __builtin_amdgcn_sched_barrier(0)
; template <class Epi, class Sched, bool ALIGN_EPI = true>
; __device__ __forceinline__ void gemm_phase(PG8_LAS unsigned char* lds, const int K, const Sched& S, const Epi& E) {
;     ...
;             PG8_WAIT_V(8); PG8_WAIT_L(0); PG8_BAR; PG8_MMA(1, 0, At, B0); PG8_MMA(1, 1, At, B1); PG8_BAR; PG8_SCHED;
;             PG8_LDB(B0, 1, 0); PG8_LDB(B1, 1, 1); PG8_SCHED; PG8_LDA(At, 1, 0); PG8_STAGE(PG8_SA(0, 1), a2 + hstep, voffA);
;             PG8_WAIT_V(8); PG8_WAIT_L(0); PG8_BAR; PG8_MMA(0, 0, At, B0); PG8_MMA(0, 1, At, B1); PG8_BAR; PG8_SCHED;
	s_setprio 1
	s_waitcnt lgkmcnt(0)
	v_mfma_f32_16x16x32_bf16 v[62:65], v[156:159], v[192:195], v[62:65]
	v_mfma_f32_16x16x32_bf16 v[58:61], v[168:171], v[192:195], v[58:61]
	v_mfma_f32_16x16x32_bf16 v[50:53], v[156:159], v[200:203], v[50:53]
	v_mfma_f32_16x16x32_bf16 v[42:45], v[168:171], v[200:203], v[42:45]
	v_mfma_f32_16x16x32_bf16 v[34:37], v[156:159], v[208:211], v[34:37]
	v_mfma_f32_16x16x32_bf16 v[26:29], v[168:171], v[208:211], v[26:29]
	v_mfma_f32_16x16x32_bf16 v[18:21], v[156:159], v[216:219], v[18:21]
	v_mfma_f32_16x16x32_bf16 v[10:13], v[168:171], v[216:219], v[10:13]
	v_mfma_f32_16x16x32_bf16 v[62:65], v[164:167], v[196:199], v[62:65]
	v_mfma_f32_16x16x32_bf16 v[58:61], v[172:175], v[196:199], v[58:61]
	v_mfma_f32_16x16x32_bf16 v[50:53], v[164:167], v[204:207], v[50:53]
	v_mfma_f32_16x16x32_bf16 v[42:45], v[172:175], v[204:207], v[42:45]
	v_mfma_f32_16x16x32_bf16 v[34:37], v[164:167], v[212:215], v[34:37]
	v_mfma_f32_16x16x32_bf16 v[26:29], v[172:175], v[212:215], v[26:29]
	v_mfma_f32_16x16x32_bf16 v[18:21], v[164:167], v[220:223], v[18:21]
	v_mfma_f32_16x16x32_bf16 v[10:13], v[172:175], v[220:223], v[10:13]
	v_mfma_f32_16x16x32_bf16 v[54:57], v[176:179], v[192:195], v[54:57]
	v_mfma_f32_16x16x32_bf16 v[46:49], v[184:187], v[192:195], v[46:49]
	v_mfma_f32_16x16x32_bf16 v[38:41], v[176:179], v[200:203], v[38:41]
	v_mfma_f32_16x16x32_bf16 v[30:33], v[184:187], v[200:203], v[30:33]
	v_mfma_f32_16x16x32_bf16 v[22:25], v[176:179], v[208:211], v[22:25]
	v_mfma_f32_16x16x32_bf16 v[14:17], v[184:187], v[208:211], v[14:17]
	v_mfma_f32_16x16x32_bf16 v[6:9], v[176:179], v[216:219], v[6:9]
	v_mfma_f32_16x16x32_bf16 v[2:5], v[184:187], v[216:219], v[2:5]
	v_mfma_f32_16x16x32_bf16 v[54:57], v[180:183], v[196:199], v[54:57]
	v_mfma_f32_16x16x32_bf16 v[46:49], v[188:191], v[196:199], v[46:49]
	v_mfma_f32_16x16x32_bf16 v[38:41], v[180:183], v[204:207], v[38:41]
	v_mfma_f32_16x16x32_bf16 v[30:33], v[188:191], v[204:207], v[30:33]
	v_mfma_f32_16x16x32_bf16 v[22:25], v[180:183], v[212:215], v[22:25]
	v_mfma_f32_16x16x32_bf16 v[14:17], v[188:191], v[212:215], v[14:17]
	v_mfma_f32_16x16x32_bf16 v[6:9], v[180:183], v[220:223], v[6:9]
	v_mfma_f32_16x16x32_bf16 v[2:5], v[188:191], v[220:223], v[2:5]
	s_setprio 0
	s_barrier
	s_add_i32 s69, 0, 0x18000
	v_add_u32_e32 v155, s69, v1
	s_add_i32 s70, 0, 0x1c000
	ds_read_b128 v[156:159], v155
	ds_read_b128 v[164:167], v155 offset:1024
	ds_read_b128 v[168:171], v155 offset:2048
	ds_read_b128 v[172:175], v155 offset:3072
	v_add_u32_e32 v155, s70, v1
	ds_read_b128 v[176:179], v155
	ds_read_b128 v[180:183], v155 offset:1024
	ds_read_b128 v[184:187], v155 offset:2048
	ds_read_b128 v[188:191], v155 offset:3072
	s_add_u32 s40, s40, 0x40000
	s_addc_u32 s41, s41, 0
	s_mov_b32 m0, s47
	v_lshl_add_u64 v[228:229], s[40:41], 0, v[130:131]
	ds_read_b128 v[192:195], v154 offset:32768
	ds_read_b128 v[196:199], v154 offset:33792
	ds_read_b128 v[200:203], v154 offset:34816
	ds_read_b128 v[204:207], v154 offset:35840
	ds_read_b128 v[208:211], v154 offset:36864
	ds_read_b128 v[212:215], v154 offset:37888
	ds_read_b128 v[216:219], v154 offset:38912
	ds_read_b128 v[220:223], v154 offset:39936
	global_load_lds_dwordx4 v[228:229], off
	s_mov_b32 m0, s48
	v_lshl_add_u64 v[228:229], s[40:41], 0, v[134:135]
	global_load_lds_dwordx4 v[228:229], off
	s_waitcnt vmcnt(8)
	s_waitcnt lgkmcnt(0)
	s_barrier
	s_setprio 1
	s_waitcnt lgkmcnt(0)
	v_mfma_f32_16x16x32_bf16 v[126:129], v[156:159], v[192:195], v[126:129]
	v_mfma_f32_16x16x32_bf16 v[122:125], v[168:171], v[192:195], v[122:125]
	v_mfma_f32_16x16x32_bf16 v[114:117], v[156:159], v[200:203], v[114:117]
	v_mfma_f32_16x16x32_bf16 v[106:109], v[168:171], v[200:203], v[106:109]
	v_mfma_f32_16x16x32_bf16 v[98:101], v[156:159], v[208:211], v[98:101]
	v_mfma_f32_16x16x32_bf16 v[90:93], v[168:171], v[208:211], v[90:93]
	v_mfma_f32_16x16x32_bf16 v[82:85], v[156:159], v[216:219], v[82:85]
	v_mfma_f32_16x16x32_bf16 v[74:77], v[168:171], v[216:219], v[74:77]
	v_mfma_f32_16x16x32_bf16 v[126:129], v[164:167], v[196:199], v[126:129]
	v_mfma_f32_16x16x32_bf16 v[122:125], v[172:175], v[196:199], v[122:125]
	v_mfma_f32_16x16x32_bf16 v[114:117], v[164:167], v[204:207], v[114:117]
	v_mfma_f32_16x16x32_bf16 v[106:109], v[172:175], v[204:207], v[106:109]
	v_mfma_f32_16x16x32_bf16 v[98:101], v[164:167], v[212:215], v[98:101]
	v_mfma_f32_16x16x32_bf16 v[90:93], v[172:175], v[212:215], v[90:93]
	v_mfma_f32_16x16x32_bf16 v[82:85], v[164:167], v[220:223], v[82:85]
	v_mfma_f32_16x16x32_bf16 v[74:77], v[172:175], v[220:223], v[74:77]
	v_mfma_f32_16x16x32_bf16 v[118:121], v[176:179], v[192:195], v[118:121]
	v_mfma_f32_16x16x32_bf16 v[110:113], v[184:187], v[192:195], v[110:113]
	v_mfma_f32_16x16x32_bf16 v[102:105], v[176:179], v[200:203], v[102:105]
	v_mfma_f32_16x16x32_bf16 v[94:97], v[184:187], v[200:203], v[94:97]
	v_mfma_f32_16x16x32_bf16 v[86:89], v[176:179], v[208:211], v[86:89]
	v_mfma_f32_16x16x32_bf16 v[78:81], v[184:187], v[208:211], v[78:81]
	v_mfma_f32_16x16x32_bf16 v[70:73], v[176:179], v[216:219], v[70:73]
	v_mfma_f32_16x16x32_bf16 v[66:69], v[184:187], v[216:219], v[66:69]
	v_mfma_f32_16x16x32_bf16 v[118:121], v[180:183], v[196:199], v[118:121]
	v_mfma_f32_16x16x32_bf16 v[110:113], v[188:191], v[196:199], v[110:113]
	v_mfma_f32_16x16x32_bf16 v[102:105], v[180:183], v[204:207], v[102:105]
	v_mfma_f32_16x16x32_bf16 v[94:97], v[188:191], v[204:207], v[94:97]
	v_mfma_f32_16x16x32_bf16 v[86:89], v[180:183], v[212:215], v[86:89]
	v_mfma_f32_16x16x32_bf16 v[78:81], v[188:191], v[212:215], v[78:81]
	v_mfma_f32_16x16x32_bf16 v[70:73], v[180:183], v[220:223], v[70:73]
	v_mfma_f32_16x16x32_bf16 v[66:69], v[188:191], v[220:223], v[66:69]
	s_setprio 0
	s_barrier
; #define PG8_STAGE(bufoff, gbase, voff) do { _Pragma("unroll") for (int _i = 0; _i < 2; ++_i) \
;         __builtin_amdgcn_global_load_lds((const unsigned*)((const char*)(gbase) + (voff)[_i]), (PG8_LAS unsigned*)(lds + (bufoff) + ldsw + _i * 8192), 16, 0, 0); } while (0)
; #define PG8_LDA(dst, b, h) do { _Pragma("unroll") for (int m = 0; m < 4; ++m) _Pragma("unroll") for (int k = 0; k < 2; ++k) dst[m][k] = *(const PG8_LAS bf16x8*)(lds + PG8_SA(b, h) + aoff + m * 2048 + k * 1024); } while (0)
; #define PG8_MMA(ai, bj, At, Bt) do { __builtin_amdgcn_s_setprio(1); _Pragma("unroll") for (int m = 0; m < 4; ++m) _Pragma("unroll") for (int n = 0; n < 2; ++n) _Pragma("unroll") for (int k = 0; k < 2; ++k) \
;         acc[ai][bj][m][n] = __builtin_amdgcn_mfma_f32_16x16x32_bf16(Bt[n][k], At[m][k], acc[ai][bj][m][n], 0, 0, 0); __builtin_amdgcn_s_setprio(0); } while (0)
; #define PG8_WAIT_V(n) asm volatile("s_waitcnt vmcnt(" #n ")" ::: "memory")
; #define PG8_WAIT_L(n) asm volatile("s_waitcnt lgkmcnt(" #n ")" ::: "memory")
; #define PG8_BAR __builtin_amdgcn_s_barrier()
; #define PG8_SCHED __builtin_amdgcn_sched_barrier(0)
; template <class Epi, class Sched, bool ALIGN_EPI = true>
; __device__ __forceinline__ void gemm_phase(PG8_LAS unsigned char* lds, const int K, const Sched& S, const Epi& E) {
;     ...
;             PG8_LDA(At, 1, 1); PG8_STAGE(PG8_SB(1, 0), b3, voffB); PG8_STAGE(PG8_SB(1, 1), b3 + hstep, voffB); PG8_STAGE(PG8_SA(1, 0), a3, voffA);
;             PG8_WAIT_V(8); PG8_WAIT_L(0); PG8_BAR; PG8_MMA(1, 0, At, B0); PG8_MMA(1, 1, At, B1); PG8_BAR; PG8_SCHED;
;         }
	s_add_i32 s40, s69, s44
	v_lshl_add_u64 v[150:151], v[150:151], 0, s[10:11]
	s_mov_b32 m0, s40
	ds_read_b128 v[192:195], v154 offset:49152
	ds_read_b128 v[196:199], v154 offset:50176
	ds_read_b128 v[200:203], v154 offset:51200
	ds_read_b128 v[204:207], v154 offset:52224
	ds_read_b128 v[208:211], v154 offset:53248
	ds_read_b128 v[212:215], v154 offset:54272
	ds_read_b128 v[216:219], v154 offset:55296
	ds_read_b128 v[220:223], v154 offset:56320
	global_load_lds_dwordx4 v[150:151], off
	s_add_i32 m0, s40, 0x2000
	s_add_u32 s38, s38, 0x40080
	v_lshl_add_u64 v[150:151], v[160:161], 0, s[10:11]
	s_addc_u32 s39, s39, 0
	s_add_i32 s40, s70, s44
	global_load_lds_dwordx4 v[150:151], off
	s_mov_b32 m0, s40
	v_lshl_add_u64 v[150:151], s[38:39], 0, v[132:133]
	global_load_lds_dwordx4 v[150:151], off
	s_add_i32 m0, s40, 0x2000
	v_lshl_add_u64 v[150:151], s[38:39], 0, v[136:137]
	global_load_lds_dwordx4 v[150:151], off
	s_mov_b32 m0, s49
	v_lshl_add_u64 v[150:151], v[224:225], 0, s[10:11]
	global_load_lds_dwordx4 v[150:151], off
	s_mov_b32 m0, s50
	v_lshl_add_u64 v[150:151], v[226:227], 0, s[10:11]
	global_load_lds_dwordx4 v[150:151], off
	s_waitcnt vmcnt(8)
	s_waitcnt lgkmcnt(0)
	s_barrier
	s_setprio 1
	s_waitcnt lgkmcnt(0)
	v_mfma_f32_16x16x32_bf16 v[62:65], v[156:159], v[192:195], v[62:65]
	v_mfma_f32_16x16x32_bf16 v[58:61], v[168:171], v[192:195], v[58:61]
	v_mfma_f32_16x16x32_bf16 v[50:53], v[156:159], v[200:203], v[50:53]
	v_mfma_f32_16x16x32_bf16 v[42:45], v[168:171], v[200:203], v[42:45]
	v_mfma_f32_16x16x32_bf16 v[34:37], v[156:159], v[208:211], v[34:37]
	v_mfma_f32_16x16x32_bf16 v[26:29], v[168:171], v[208:211], v[26:29]
	v_mfma_f32_16x16x32_bf16 v[18:21], v[156:159], v[216:219], v[18:21]
	v_mfma_f32_16x16x32_bf16 v[10:13], v[168:171], v[216:219], v[10:13]
	v_mfma_f32_16x16x32_bf16 v[62:65], v[164:167], v[196:199], v[62:65]
	v_mfma_f32_16x16x32_bf16 v[58:61], v[172:175], v[196:199], v[58:61]
	v_mfma_f32_16x16x32_bf16 v[50:53], v[164:167], v[204:207], v[50:53]
	v_mfma_f32_16x16x32_bf16 v[42:45], v[172:175], v[204:207], v[42:45]
	v_mfma_f32_16x16x32_bf16 v[34:37], v[164:167], v[212:215], v[34:37]
	v_mfma_f32_16x16x32_bf16 v[26:29], v[172:175], v[212:215], v[26:29]
	v_mfma_f32_16x16x32_bf16 v[18:21], v[164:167], v[220:223], v[18:21]
	v_mfma_f32_16x16x32_bf16 v[10:13], v[172:175], v[220:223], v[10:13]
	v_mfma_f32_16x16x32_bf16 v[54:57], v[176:179], v[192:195], v[54:57]
	v_mfma_f32_16x16x32_bf16 v[46:49], v[184:187], v[192:195], v[46:49]
	v_mfma_f32_16x16x32_bf16 v[38:41], v[176:179], v[200:203], v[38:41]
	v_mfma_f32_16x16x32_bf16 v[30:33], v[184:187], v[200:203], v[30:33]
	v_mfma_f32_16x16x32_bf16 v[22:25], v[176:179], v[208:211], v[22:25]
	v_mfma_f32_16x16x32_bf16 v[14:17], v[184:187], v[208:211], v[14:17]
	v_mfma_f32_16x16x32_bf16 v[6:9], v[176:179], v[216:219], v[6:9]
	v_mfma_f32_16x16x32_bf16 v[2:5], v[184:187], v[216:219], v[2:5]
	v_mfma_f32_16x16x32_bf16 v[54:57], v[180:183], v[196:199], v[54:57]
	v_mfma_f32_16x16x32_bf16 v[46:49], v[188:191], v[196:199], v[46:49]
	v_mfma_f32_16x16x32_bf16 v[38:41], v[180:183], v[204:207], v[38:41]
	v_mfma_f32_16x16x32_bf16 v[30:33], v[188:191], v[204:207], v[30:33]
	v_mfma_f32_16x16x32_bf16 v[22:25], v[180:183], v[212:215], v[22:25]
	v_mfma_f32_16x16x32_bf16 v[14:17], v[188:191], v[212:215], v[14:17]
	v_mfma_f32_16x16x32_bf16 v[6:9], v[180:183], v[220:223], v[6:9]
	v_mfma_f32_16x16x32_bf16 v[2:5], v[188:191], v[220:223], v[2:5]
	s_setprio 0
	s_barrier
	s_add_i32 s68, s68, 2
	s_add_u32 s36, s36, 0x100
	s_addc_u32 s37, s37, 0
	s_add_u32 s66, s66, 0x100
	s_addc_u32 s67, s67, 0
	s_cmp_gt_u32 s68, 13
	s_cbranch_scc0 .LBB0_1713
	s_and_b64 vcc, exec, s[12:13]
	s_cbranch_vccz .LBB0_1716
	s_barrier

; #define PG8_STAGE(bufoff, gbase, voff) do { _Pragma("unroll") for (int _i = 0; _i < 2; ++_i) \
;         __builtin_amdgcn_global_load_lds((const unsigned*)((const char*)(gbase) + (voff)[_i]), (PG8_LAS unsigned*)(lds + (bufoff) + ldsw + _i * 8192), 16, 0, 0); } while (0)
; #define PG8_LDA(dst, b, h) do { _Pragma("unroll") for (int m = 0; m < 4; ++m) _Pragma("unroll") for (int k = 0; k < 2; ++k) dst[m][k] = *(const PG8_LAS bf16x8*)(lds + PG8_SA(b, h) + aoff + m * 2048 + k * 1024); } while (0)
; #define PG8_LDB(dst, b, h) do { _Pragma("unroll") for (int n = 0; n < 2; ++n) _Pragma("unroll") for (int k = 0; k < 2; ++k) dst[n][k] = *(const PG8_LAS bf16x8*)(lds + PG8_SB(b, h) + boff + n * 2048 + k * 1024); } while (0)
; #define PG8_MMA(ai, bj, At, Bt) do { __builtin_amdgcn_s_setprio(1); _Pragma("unroll") for (int m = 0; m < 4; ++m) _Pragma("unroll") for (int n = 0; n < 2; ++n) _Pragma("unroll") for (int k = 0; k < 2; ++k) \
;         acc[ai][bj][m][n] = __builtin_amdgcn_mfma_f32_16x16x32_bf16(Bt[n][k], At[m][k], acc[ai][bj][m][n], 0, 0, 0); __builtin_amdgcn_s_setprio(0); } while (0)
; #define PG8_WAIT_V(n) asm volatile("s_waitcnt vmcnt(" #n ")" ::: "memory")
; #define PG8_WAIT_L(n) asm volatile("s_waitcnt lgkmcnt(" #n ")" ::: "memory")
; #define PG8_BAR __builtin_amdgcn_s_barrier()
; #define PG8_SCHED __builtin_amdgcn_sched_barrier(0)
; template <class Epi, class Sched, bool ALIGN_EPI = true>
; __device__ __forceinline__ void gemm_phase(PG8_LAS unsigned char* lds, const int K, const Sched& S, const Epi& E) {
;     ...
;         for (int t = 0; t < nt; t += 2) {
;             const bool last = (t == nt - 2);
;             const char* a1 = cA + (size_t)(t + 1) * kstep;
;             const char* a2 = last ? nA : cA + (size_t)(t + 2) * kstep; const char* b2 = last ? nB : cB + (size_t)(t + 2) * kstep;
;             const char* a3 = a2 + kstep; const char* b3 = b2 + kstep;
;             PG8_LDB(B0, 0, 0); PG8_LDB(B1, 0, 1); PG8_SCHED; PG8_LDA(At, 0, 0); PG8_STAGE(PG8_SA(1, 1), a1 + hstep, voffA);
;             PG8_WAIT_V(8); PG8_WAIT_L(0); PG8_BAR; PG8_MMA(0, 0, At, B0); PG8_MMA(0, 1, At, B1); PG8_BAR; PG8_SCHED;
;             PG8_LDA(At, 0, 1); PG8_STAGE(PG8_SB(0, 0), b2, voffB); PG8_STAGE(PG8_SB(0, 1), b2 + hstep, voffB); PG8_STAGE(PG8_SA(0, 0), a2, voffA);
;             PG8_WAIT_V(8); PG8_WAIT_L(0); PG8_BAR; PG8_MMA(1, 0, At, B0); PG8_MMA(1, 1, At, B1); PG8_BAR; PG8_SCHED;
.LBB0_1814:
	ds_read_b128 v[128:131], v179
	ds_read_b128 v[132:135], v179 offset:1024
	ds_read_b128 v[136:139], v179 offset:2048
	ds_read_b128 v[140:143], v179 offset:3072
	ds_read_b128 v[144:147], v180
	ds_read_b128 v[162:165], v180 offset:1024
	ds_read_b128 v[166:169], v180 offset:2048
	ds_read_b128 v[170:173], v180 offset:3072
	s_add_u32 s56, s54, 0xfff00080
	s_addc_u32 s57, s55, -1
	s_cmp_eq_u32 s93, 60
	s_cselect_b32 s59, s11, s57
	s_cselect_b32 s58, s43, s56
	s_cselect_b32 s57, s41, s92
	s_cselect_b32 s56, s51, s91
	v_lshl_add_u64 v[222:223], s[54:55], 0, v[154:155]
	s_add_i32 m0, s63, 0xc000
	ds_read_b128 v[190:193], v181
	ds_read_b128 v[194:197], v181 offset:1024
	ds_read_b128 v[198:201], v181 offset:2048
	ds_read_b128 v[202:205], v181 offset:3072
	ds_read_b128 v[206:209], v181 offset:4096
	ds_read_b128 v[210:213], v181 offset:5120
	ds_read_b128 v[214:217], v181 offset:6144
	ds_read_b128 v[218:221], v181 offset:7168
	global_load_lds_dwordx4 v[222:223], off
	s_add_i32 m0, s63, 0xe000
	v_lshl_add_u64 v[222:223], s[54:55], 0, v[156:157]
	global_load_lds_dwordx4 v[222:223], off
	s_waitcnt vmcnt(8)
	s_waitcnt lgkmcnt(0)
	s_barrier
	s_setprio 1
	s_waitcnt lgkmcnt(0)
	v_mfma_f32_16x16x32_bf16 v[56:59], v[128:131], v[190:193], v[56:59]
	v_mfma_f32_16x16x32_bf16 v[32:35], v[136:139], v[190:193], v[32:35]
	v_mfma_f32_16x16x32_bf16 v[72:75], v[128:131], v[198:201], v[72:75]
	v_mfma_f32_16x16x32_bf16 v[44:47], v[136:139], v[198:201], v[44:47]
	v_mfma_f32_16x16x32_bf16 v[84:87], v[128:131], v[206:209], v[84:87]
	v_mfma_f32_16x16x32_bf16 v[52:55], v[136:139], v[206:209], v[52:55]
	v_mfma_f32_16x16x32_bf16 v[108:111], v[128:131], v[214:217], v[108:111]
	v_mfma_f32_16x16x32_bf16 v[64:67], v[136:139], v[214:217], v[64:67]
	v_mfma_f32_16x16x32_bf16 v[56:59], v[132:135], v[194:197], v[56:59]
	v_mfma_f32_16x16x32_bf16 v[32:35], v[140:143], v[194:197], v[32:35]
	v_mfma_f32_16x16x32_bf16 v[72:75], v[132:135], v[202:205], v[72:75]
	v_mfma_f32_16x16x32_bf16 v[44:47], v[140:143], v[202:205], v[44:47]
	v_mfma_f32_16x16x32_bf16 v[84:87], v[132:135], v[210:213], v[84:87]
	v_mfma_f32_16x16x32_bf16 v[52:55], v[140:143], v[210:213], v[52:55]
	v_mfma_f32_16x16x32_bf16 v[108:111], v[132:135], v[218:221], v[108:111]
	v_mfma_f32_16x16x32_bf16 v[64:67], v[140:143], v[218:221], v[64:67]
	v_mfma_f32_16x16x32_bf16 v[12:15], v[144:147], v[190:193], v[12:15]
	v_mfma_f32_16x16x32_bf16 v[0:3], v[166:169], v[190:193], v[0:3]
	v_mfma_f32_16x16x32_bf16 v[20:23], v[144:147], v[198:201], v[20:23]
	v_mfma_f32_16x16x32_bf16 v[4:7], v[166:169], v[198:201], v[4:7]
	v_mfma_f32_16x16x32_bf16 v[28:31], v[144:147], v[206:209], v[28:31]
	v_mfma_f32_16x16x32_bf16 v[8:11], v[166:169], v[206:209], v[8:11]
	v_mfma_f32_16x16x32_bf16 v[40:43], v[144:147], v[214:217], v[40:43]
	v_mfma_f32_16x16x32_bf16 v[16:19], v[166:169], v[214:217], v[16:19]
	v_mfma_f32_16x16x32_bf16 v[12:15], v[162:165], v[194:197], v[12:15]
	v_mfma_f32_16x16x32_bf16 v[0:3], v[170:173], v[194:197], v[0:3]
	v_mfma_f32_16x16x32_bf16 v[20:23], v[162:165], v[202:205], v[20:23]
	v_mfma_f32_16x16x32_bf16 v[4:7], v[170:173], v[202:205], v[4:7]
	v_mfma_f32_16x16x32_bf16 v[28:31], v[162:165], v[210:213], v[28:31]
	v_mfma_f32_16x16x32_bf16 v[8:11], v[170:173], v[210:213], v[8:11]
	v_mfma_f32_16x16x32_bf16 v[40:43], v[162:165], v[218:221], v[40:43]
	v_mfma_f32_16x16x32_bf16 v[16:19], v[170:173], v[218:221], v[16:19]
	s_setprio 0
	s_barrier
	s_add_i32 s94, s76, s62
	v_lshl_add_u64 v[222:223], s[56:57], 0, v[148:149]
	s_mov_b32 m0, s94
	ds_read_b128 v[190:193], v181 offset:16384
	ds_read_b128 v[194:197], v181 offset:17408
	ds_read_b128 v[198:201], v181 offset:18432
	ds_read_b128 v[202:205], v181 offset:19456
	ds_read_b128 v[206:209], v181 offset:20480
	ds_read_b128 v[210:213], v181 offset:21504
	ds_read_b128 v[214:217], v181 offset:22528
	ds_read_b128 v[218:221], v181 offset:23552
	global_load_lds_dwordx4 v[222:223], off
	s_add_i32 m0, s94, 0x2000
	s_add_u32 s94, s56, 0x100000
	v_lshl_add_u64 v[224:225], s[56:57], 0, v[150:151]
	s_addc_u32 s95, s57, 0
	s_add_i32 s96, s77, s62
	global_load_lds_dwordx4 v[224:225], off
	v_lshl_add_u64 v[226:227], s[94:95], 0, v[148:149]
	s_mov_b32 m0, s96
	v_lshl_add_u64 v[228:229], s[58:59], 0, v[150:151]
	global_load_lds_dwordx4 v[226:227], off
	s_add_i32 m0, s96, 0x2000
	v_lshl_add_u64 v[226:227], s[94:95], 0, v[150:151]
	global_load_lds_dwordx4 v[226:227], off
	s_mov_b32 m0, s63
	v_lshl_add_u64 v[226:227], s[58:59], 0, v[148:149]
	global_load_lds_dwordx4 v[226:227], off
	s_mov_b32 m0, s64
	s_nop 0
	global_load_lds_dwordx4 v[228:229], off
	s_waitcnt vmcnt(8)
	s_waitcnt lgkmcnt(0)
	s_barrier
; #define PG8_STAGE(bufoff, gbase, voff) do { _Pragma("unroll") for (int _i = 0; _i < 2; ++_i) \
;         __builtin_amdgcn_global_load_lds((const unsigned*)((const char*)(gbase) + (voff)[_i]), (PG8_LAS unsigned*)(lds + (bufoff) + ldsw + _i * 8192), 16, 0, 0); } while (0)
; #define PG8_LDA(dst, b, h) do { _Pragma("unroll") for (int m = 0; m < 4; ++m) _Pragma("unroll") for (int k = 0; k < 2; ++k) dst[m][k] = *(const PG8_LAS bf16x8*)(lds + PG8_SA(b, h) + aoff + m * 2048 + k * 1024); } while (0)
; #define PG8_LDB(dst, b, h) do { _Pragma("unroll") for (int n = 0; n < 2; ++n) _Pragma("unroll") for (int k = 0; k < 2; ++k) dst[n][k] = *(const PG8_LAS bf16x8*)(lds + PG8_SB(b, h) + boff + n * 2048 + k * 1024); } while (0)
; #define PG8_MMA(ai, bj, At, Bt) do { __builtin_amdgcn_s_setprio(1); _Pragma("unroll") for (int m = 0; m < 4; ++m) _Pragma("unroll") for (int n = 0; n < 2; ++n) _Pragma("unroll") for (int k = 0; k < 2; ++k) \
;         acc[ai][bj][m][n] = __builtin_amdgcn_mfma_f32_16x16x32_bf16(Bt[n][k], At[m][k], acc[ai][bj][m][n], 0, 0, 0); __builtin_amdgcn_s_setprio(0); } while (0)
; #define PG8_WAIT_V(n) asm volatile("s_waitcnt vmcnt(" #n ")" ::: "memory")
; #define PG8_WAIT_L(n) asm volatile("s_waitcnt lgkmcnt(" #n ")" ::: "memory")
; #define PG8_BAR __builtin_amdgcn_s_barrier()
; #define PG8_SCHED __builtin_amdgcn_sched_barrier(0)
; template <class Epi, class Sched, bool ALIGN_EPI = true>
; __device__ __forceinline__ void gemm_phase(PG8_LAS unsigned char* lds, const int K, const Sched& S, const Epi& E) {
;     ...
;             PG8_WAIT_V(8); PG8_WAIT_L(0); PG8_BAR; PG8_MMA(1, 0, At, B0); PG8_MMA(1, 1, At, B1); PG8_BAR; PG8_SCHED;
;             PG8_LDB(B0, 1, 0); PG8_LDB(B1, 1, 1); PG8_SCHED; PG8_LDA(At, 1, 0); PG8_STAGE(PG8_SA(0, 1), a2 + hstep, voffA);
;             PG8_WAIT_V(8); PG8_WAIT_L(0); PG8_BAR; PG8_MMA(0, 0, At, B0); PG8_MMA(0, 1, At, B1); PG8_BAR; PG8_SCHED;
	s_setprio 1
	s_waitcnt lgkmcnt(0)
	v_mfma_f32_16x16x32_bf16 v[112:115], v[128:131], v[190:193], v[112:115]
	v_mfma_f32_16x16x32_bf16 v[76:79], v[136:139], v[190:193], v[76:79]
	v_mfma_f32_16x16x32_bf16 v[124:127], v[128:131], v[198:201], v[124:127]
	v_mfma_f32_16x16x32_bf16 v[88:91], v[136:139], v[198:201], v[88:91]
	v_mfma_f32_16x16x32_bf16 v[120:123], v[128:131], v[206:209], v[120:123]
	v_mfma_f32_16x16x32_bf16 v[116:119], v[136:139], v[206:209], v[116:119]
	v_mfma_f32_16x16x32_bf16 v[104:107], v[128:131], v[214:217], v[104:107]
	v_mfma_f32_16x16x32_bf16 v[100:103], v[136:139], v[214:217], v[100:103]
	v_mfma_f32_16x16x32_bf16 v[112:115], v[132:135], v[194:197], v[112:115]
	v_mfma_f32_16x16x32_bf16 v[76:79], v[140:143], v[194:197], v[76:79]
	v_mfma_f32_16x16x32_bf16 v[124:127], v[132:135], v[202:205], v[124:127]
	v_mfma_f32_16x16x32_bf16 v[88:91], v[140:143], v[202:205], v[88:91]
	v_mfma_f32_16x16x32_bf16 v[120:123], v[132:135], v[210:213], v[120:123]
	v_mfma_f32_16x16x32_bf16 v[116:119], v[140:143], v[210:213], v[116:119]
	v_mfma_f32_16x16x32_bf16 v[104:107], v[132:135], v[218:221], v[104:107]
	v_mfma_f32_16x16x32_bf16 v[100:103], v[140:143], v[218:221], v[100:103]
	v_mfma_f32_16x16x32_bf16 v[48:51], v[144:147], v[190:193], v[48:51]
	v_mfma_f32_16x16x32_bf16 v[24:27], v[166:169], v[190:193], v[24:27]
	v_mfma_f32_16x16x32_bf16 v[60:63], v[144:147], v[198:201], v[60:63]
	v_mfma_f32_16x16x32_bf16 v[36:39], v[166:169], v[198:201], v[36:39]
	v_mfma_f32_16x16x32_bf16 v[96:99], v[144:147], v[206:209], v[96:99]
	v_mfma_f32_16x16x32_bf16 v[68:71], v[166:169], v[206:209], v[68:71]
	v_mfma_f32_16x16x32_bf16 v[92:95], v[144:147], v[214:217], v[92:95]
	v_mfma_f32_16x16x32_bf16 v[80:83], v[166:169], v[214:217], v[80:83]
	v_mfma_f32_16x16x32_bf16 v[48:51], v[162:165], v[194:197], v[48:51]
	v_mfma_f32_16x16x32_bf16 v[24:27], v[170:173], v[194:197], v[24:27]
	v_mfma_f32_16x16x32_bf16 v[60:63], v[162:165], v[202:205], v[60:63]
	v_mfma_f32_16x16x32_bf16 v[36:39], v[170:173], v[202:205], v[36:39]
	v_mfma_f32_16x16x32_bf16 v[96:99], v[162:165], v[210:213], v[96:99]
	v_mfma_f32_16x16x32_bf16 v[68:71], v[170:173], v[210:213], v[68:71]
	v_mfma_f32_16x16x32_bf16 v[92:95], v[162:165], v[218:221], v[92:95]
	v_mfma_f32_16x16x32_bf16 v[80:83], v[170:173], v[218:221], v[80:83]
	s_setprio 0
	s_barrier
	s_add_i32 s94, 0, 0x18000
	s_add_i32 s95, 0, 0x1c000
	v_add_u32_e32 v140, s94, v174
	v_add_u32_e32 v170, s95, v174
	ds_read_b128 v[128:131], v140
	ds_read_b128 v[132:135], v140 offset:1024
	ds_read_b128 v[136:139], v140 offset:2048
	ds_read_b128 v[140:143], v140 offset:3072
	ds_read_b128 v[144:147], v170
	ds_read_b128 v[162:165], v170 offset:1024
	ds_read_b128 v[166:169], v170 offset:2048
	ds_read_b128 v[170:173], v170 offset:3072
	s_add_u32 s58, s58, 0x100000
	s_addc_u32 s59, s59, 0
	s_mov_b32 m0, s65
	v_lshl_add_u64 v[230:231], s[58:59], 0, v[148:149]
	ds_read_b128 v[190:193], v181 offset:32768
	ds_read_b128 v[194:197], v181 offset:33792
	ds_read_b128 v[198:201], v181 offset:34816
	ds_read_b128 v[202:205], v181 offset:35840
	ds_read_b128 v[206:209], v181 offset:36864
	ds_read_b128 v[210:213], v181 offset:37888
	ds_read_b128 v[214:217], v181 offset:38912
	ds_read_b128 v[218:221], v181 offset:39936
	global_load_lds_dwordx4 v[230:231], off
	s_mov_b32 m0, s66
	v_lshl_add_u64 v[230:231], s[58:59], 0, v[150:151]
	global_load_lds_dwordx4 v[230:231], off
	s_waitcnt vmcnt(8)
	s_waitcnt lgkmcnt(0)
	s_barrier
	s_setprio 1
	s_waitcnt lgkmcnt(0)
	v_mfma_f32_16x16x32_bf16 v[56:59], v[128:131], v[190:193], v[56:59]
	v_mfma_f32_16x16x32_bf16 v[32:35], v[136:139], v[190:193], v[32:35]
	v_mfma_f32_16x16x32_bf16 v[72:75], v[128:131], v[198:201], v[72:75]
	v_mfma_f32_16x16x32_bf16 v[44:47], v[136:139], v[198:201], v[44:47]
	v_mfma_f32_16x16x32_bf16 v[84:87], v[128:131], v[206:209], v[84:87]
	v_mfma_f32_16x16x32_bf16 v[52:55], v[136:139], v[206:209], v[52:55]
	v_mfma_f32_16x16x32_bf16 v[108:111], v[128:131], v[214:217], v[108:111]
	v_mfma_f32_16x16x32_bf16 v[64:67], v[136:139], v[214:217], v[64:67]
	v_mfma_f32_16x16x32_bf16 v[56:59], v[132:135], v[194:197], v[56:59]
	v_mfma_f32_16x16x32_bf16 v[32:35], v[140:143], v[194:197], v[32:35]
	v_mfma_f32_16x16x32_bf16 v[72:75], v[132:135], v[202:205], v[72:75]
	v_mfma_f32_16x16x32_bf16 v[44:47], v[140:143], v[202:205], v[44:47]
	v_mfma_f32_16x16x32_bf16 v[84:87], v[132:135], v[210:213], v[84:87]
	v_mfma_f32_16x16x32_bf16 v[52:55], v[140:143], v[210:213], v[52:55]
	v_mfma_f32_16x16x32_bf16 v[108:111], v[132:135], v[218:221], v[108:111]
	v_mfma_f32_16x16x32_bf16 v[64:67], v[140:143], v[218:221], v[64:67]
	v_mfma_f32_16x16x32_bf16 v[12:15], v[144:147], v[190:193], v[12:15]
	v_mfma_f32_16x16x32_bf16 v[0:3], v[166:169], v[190:193], v[0:3]
	v_mfma_f32_16x16x32_bf16 v[20:23], v[144:147], v[198:201], v[20:23]
	v_mfma_f32_16x16x32_bf16 v[4:7], v[166:169], v[198:201], v[4:7]
	v_mfma_f32_16x16x32_bf16 v[28:31], v[144:147], v[206:209], v[28:31]
	v_mfma_f32_16x16x32_bf16 v[8:11], v[166:169], v[206:209], v[8:11]
	v_mfma_f32_16x16x32_bf16 v[40:43], v[144:147], v[214:217], v[40:43]
	v_mfma_f32_16x16x32_bf16 v[16:19], v[166:169], v[214:217], v[16:19]
	v_mfma_f32_16x16x32_bf16 v[12:15], v[162:165], v[194:197], v[12:15]
	v_mfma_f32_16x16x32_bf16 v[0:3], v[170:173], v[194:197], v[0:3]
	v_mfma_f32_16x16x32_bf16 v[20:23], v[162:165], v[202:205], v[20:23]
	v_mfma_f32_16x16x32_bf16 v[4:7], v[170:173], v[202:205], v[4:7]
	v_mfma_f32_16x16x32_bf16 v[28:31], v[162:165], v[210:213], v[28:31]
	v_mfma_f32_16x16x32_bf16 v[8:11], v[170:173], v[210:213], v[8:11]
	v_mfma_f32_16x16x32_bf16 v[40:43], v[162:165], v[218:221], v[40:43]
	v_mfma_f32_16x16x32_bf16 v[16:19], v[170:173], v[218:221], v[16:19]
	s_setprio 0
	s_barrier
; #define PG8_STAGE(bufoff, gbase, voff) do { _Pragma("unroll") for (int _i = 0; _i < 2; ++_i) \
;         __builtin_amdgcn_global_load_lds((const unsigned*)((const char*)(gbase) + (voff)[_i]), (PG8_LAS unsigned*)(lds + (bufoff) + ldsw + _i * 8192), 16, 0, 0); } while (0)
; #define PG8_LDA(dst, b, h) do { _Pragma("unroll") for (int m = 0; m < 4; ++m) _Pragma("unroll") for (int k = 0; k < 2; ++k) dst[m][k] = *(const PG8_LAS bf16x8*)(lds + PG8_SA(b, h) + aoff + m * 2048 + k * 1024); } while (0)
; #define PG8_MMA(ai, bj, At, Bt) do { __builtin_amdgcn_s_setprio(1); _Pragma("unroll") for (int m = 0; m < 4; ++m) _Pragma("unroll") for (int n = 0; n < 2; ++n) _Pragma("unroll") for (int k = 0; k < 2; ++k) \
;         acc[ai][bj][m][n] = __builtin_amdgcn_mfma_f32_16x16x32_bf16(Bt[n][k], At[m][k], acc[ai][bj][m][n], 0, 0, 0); __builtin_amdgcn_s_setprio(0); } while (0)
; #define PG8_WAIT_V(n) asm volatile("s_waitcnt vmcnt(" #n ")" ::: "memory")
; #define PG8_WAIT_L(n) asm volatile("s_waitcnt lgkmcnt(" #n ")" ::: "memory")
; #define PG8_BAR __builtin_amdgcn_s_barrier()
; #define PG8_SCHED __builtin_amdgcn_sched_barrier(0)
; template <class Epi, class Sched, bool ALIGN_EPI = true>
; __device__ __forceinline__ void gemm_phase(PG8_LAS unsigned char* lds, const int K, const Sched& S, const Epi& E) {
;     ...
;             PG8_LDA(At, 1, 1); PG8_STAGE(PG8_SB(1, 0), b3, voffB); PG8_STAGE(PG8_SB(1, 1), b3 + hstep, voffB); PG8_STAGE(PG8_SA(1, 0), a3, voffA);
;             PG8_WAIT_V(8); PG8_WAIT_L(0); PG8_BAR; PG8_MMA(1, 0, At, B0); PG8_MMA(1, 1, At, B1); PG8_BAR; PG8_SCHED;
;         }
	s_add_i32 s58, s94, s62
	v_lshl_add_u64 v[222:223], v[222:223], 0, s[20:21]
	s_mov_b32 m0, s58
	ds_read_b128 v[190:193], v181 offset:49152
	ds_read_b128 v[194:197], v181 offset:50176
	ds_read_b128 v[198:201], v181 offset:51200
	ds_read_b128 v[202:205], v181 offset:52224
	ds_read_b128 v[206:209], v181 offset:53248
	ds_read_b128 v[210:213], v181 offset:54272
	ds_read_b128 v[214:217], v181 offset:55296
	ds_read_b128 v[218:221], v181 offset:56320
	global_load_lds_dwordx4 v[222:223], off
	s_add_i32 m0, s58, 0x2000
	s_add_u32 s56, s56, 0x100080
	v_lshl_add_u64 v[222:223], v[224:225], 0, s[20:21]
	s_addc_u32 s57, s57, 0
	s_add_i32 s58, s95, s62
	global_load_lds_dwordx4 v[222:223], off
	s_mov_b32 m0, s58
	v_lshl_add_u64 v[222:223], s[56:57], 0, v[148:149]
	global_load_lds_dwordx4 v[222:223], off
	s_add_i32 m0, s58, 0x2000
	v_lshl_add_u64 v[222:223], s[56:57], 0, v[150:151]
	global_load_lds_dwordx4 v[222:223], off
	s_mov_b32 m0, s70
	v_lshl_add_u64 v[222:223], v[226:227], 0, s[20:21]
	global_load_lds_dwordx4 v[222:223], off
	s_mov_b32 m0, s71
	v_lshl_add_u64 v[222:223], v[228:229], 0, s[20:21]
	global_load_lds_dwordx4 v[222:223], off
	s_waitcnt vmcnt(8)
	s_waitcnt lgkmcnt(0)
	s_barrier
	s_setprio 1
	s_waitcnt lgkmcnt(0)
	v_mfma_f32_16x16x32_bf16 v[112:115], v[128:131], v[190:193], v[112:115]
	v_mfma_f32_16x16x32_bf16 v[76:79], v[136:139], v[190:193], v[76:79]
	v_mfma_f32_16x16x32_bf16 v[124:127], v[128:131], v[198:201], v[124:127]
	v_mfma_f32_16x16x32_bf16 v[88:91], v[136:139], v[198:201], v[88:91]
	v_mfma_f32_16x16x32_bf16 v[120:123], v[128:131], v[206:209], v[120:123]
	v_mfma_f32_16x16x32_bf16 v[116:119], v[136:139], v[206:209], v[116:119]
	v_mfma_f32_16x16x32_bf16 v[104:107], v[128:131], v[214:217], v[104:107]
	v_mfma_f32_16x16x32_bf16 v[100:103], v[136:139], v[214:217], v[100:103]
	v_mfma_f32_16x16x32_bf16 v[112:115], v[132:135], v[194:197], v[112:115]
	v_mfma_f32_16x16x32_bf16 v[76:79], v[140:143], v[194:197], v[76:79]
	v_mfma_f32_16x16x32_bf16 v[124:127], v[132:135], v[202:205], v[124:127]
	v_mfma_f32_16x16x32_bf16 v[88:91], v[140:143], v[202:205], v[88:91]
	v_mfma_f32_16x16x32_bf16 v[120:123], v[132:135], v[210:213], v[120:123]
	v_mfma_f32_16x16x32_bf16 v[116:119], v[140:143], v[210:213], v[116:119]
	v_mfma_f32_16x16x32_bf16 v[104:107], v[132:135], v[218:221], v[104:107]
	v_mfma_f32_16x16x32_bf16 v[100:103], v[140:143], v[218:221], v[100:103]
	v_mfma_f32_16x16x32_bf16 v[48:51], v[144:147], v[190:193], v[48:51]
	v_mfma_f32_16x16x32_bf16 v[24:27], v[166:169], v[190:193], v[24:27]
	v_mfma_f32_16x16x32_bf16 v[60:63], v[144:147], v[198:201], v[60:63]
	v_mfma_f32_16x16x32_bf16 v[36:39], v[166:169], v[198:201], v[36:39]
	v_mfma_f32_16x16x32_bf16 v[96:99], v[144:147], v[206:209], v[96:99]
	v_mfma_f32_16x16x32_bf16 v[68:71], v[166:169], v[206:209], v[68:71]
	v_mfma_f32_16x16x32_bf16 v[92:95], v[144:147], v[214:217], v[92:95]
	v_mfma_f32_16x16x32_bf16 v[80:83], v[166:169], v[214:217], v[80:83]
	v_mfma_f32_16x16x32_bf16 v[48:51], v[162:165], v[194:197], v[48:51]
	v_mfma_f32_16x16x32_bf16 v[24:27], v[170:173], v[194:197], v[24:27]
	v_mfma_f32_16x16x32_bf16 v[60:63], v[162:165], v[202:205], v[60:63]
	v_mfma_f32_16x16x32_bf16 v[36:39], v[170:173], v[202:205], v[36:39]
	v_mfma_f32_16x16x32_bf16 v[96:99], v[162:165], v[210:213], v[96:99]
	v_mfma_f32_16x16x32_bf16 v[68:71], v[170:173], v[210:213], v[68:71]
	v_mfma_f32_16x16x32_bf16 v[92:95], v[162:165], v[218:221], v[92:95]
	v_mfma_f32_16x16x32_bf16 v[80:83], v[170:173], v[218:221], v[80:83]
	s_setprio 0
	s_barrier
	s_add_i32 s93, s93, 2
	s_add_u32 s54, s54, 0x100
	s_addc_u32 s55, s55, 0
	s_add_u32 s91, s91, 0x100
	s_addc_u32 s92, s92, 0
	s_cmp_gt_u32 s93, 61
	s_cbranch_scc0 .LBB0_1814
	s_and_b64 vcc, exec, s[22:23]
	s_cbranch_vccz .LBB0_1817
	s_barrier
